# GEMM loops: MFMA order within each k-group made boustrophedon so each step changes one operand only (power probe), on top of epilogue/logf edits
# speedup vs baseline: 1.0071x; 1.0071x over previous
; #define PG8_STAGE(bufoff, gbase, voff) do { _Pragma("unroll") for (int _i = 0; _i < 2; ++_i) \
;         __builtin_amdgcn_global_load_lds((const unsigned*)((const char*)(gbase) + (voff)[_i]), (LAS unsigned*)(lds + (bufoff) + ldsw + _i * 8192), 16, 0, 0); } while (0)
; #define PG8_LDA(dst, b, h) do { _Pragma("unroll") for (int m = 0; m < 4; ++m) _Pragma("unroll") for (int k = 0; k < 2; ++k) dst[m][k] = *(const LAS bf16x8*)(lds + PG8_SA(b, h) + aoff + m * 2048 + k * 1024); } while (0)
; #define PG8_LDB(dst, b, h) do { _Pragma("unroll") for (int n = 0; n < 2; ++n) _Pragma("unroll") for (int k = 0; k < 2; ++k) dst[n][k] = *(const LAS bf16x8*)(lds + PG8_SB(b, h) + boff + n * 2048 + k * 1024); } while (0)
; #define PG8_MMA(ai, bj, At, Bt) do { __builtin_amdgcn_s_setprio(1); _Pragma("unroll") for (int m = 0; m < 4; ++m) _Pragma("unroll") for (int n = 0; n < 2; ++n) _Pragma("unroll") for (int k = 0; k < 2; ++k) \
;         acc[ai][bj][m][n] = __builtin_amdgcn_mfma_f32_16x16x32_bf16(Bt[n][k], At[m][k], acc[ai][bj][m][n], 0, 0, 0); __builtin_amdgcn_s_setprio(0); } while (0)
; #define PG8_WAIT_V(n) asm volatile("s_waitcnt vmcnt(" #n ")" ::: "memory")
; #define PG8_WAIT_L(n) asm volatile("s_waitcnt lgkmcnt(" #n ")" ::: "memory")
; template <class Epi, class Sched, bool ALIGN_EPI = false, bool SP2 = false>
; __device__ __forceinline__ void gemm_phase(LAS unsigned char* lds, const Gemm g, const Sched& S, const Epi& E) {
;     ...
;         for (int t = 0; t < nt; t += 2) {
;             const bool last = (t == nt - 2);
;             const char* a1 = cA + (size_t)(t + 1) * kstep;
;             const char* a2 = last ? nA : cA + (size_t)(t + 2) * kstep; const char* b2 = last ? nB : cB + (size_t)(t + 2) * kstep;
;             const char* a3 = a2 + kstep; const char* b3 = b2 + kstep;
;             if (last && has_next) S.a_ready(nxt);
;             if constexpr (SP2) {
;             PG8_LDB(B0, 0, 0); PG8_LDB(B1, 0, 1); PG8_SCHED; PG8_LDA(At, 0, 0); PG8_STAGE(PG8_SA(1, 1), a1 + hstep, voffA);
;             PG8_WAIT_V(8); PG8_WAIT_L(0); PG8_BAR; PG8_MMA(0, 0, At, B0); PG8_MMA(0, 1, At, B1); PG8_BAR; PG8_SCHED;
;             PG8_LDA(At, 0, 1); PG8_STAGE(PG8_SB(0, 0), b2, voffB); PG8_STAGE(PG8_SB(0, 1), b2 + hstep, voffB); PG8_STAGE(PG8_SA(0, 0), a2, voffA);
;             PG8_WAIT_V(8); PG8_WAIT_L(0); PG8_BAR; PG8_MMA(1, 0, At, B0); PG8_MMA(1, 1, At, B1); PG8_BAR; PG8_SCHED;
.LBB0_173:
	s_add_u32 s26, s24, 0xfff80080
	s_addc_u32 s27, s25, -1
	s_add_i32 s45, 0, 0x10000
	s_cmp_eq_u32 s44, 28
	s_cselect_b32 s29, s7, s27
	s_cselect_b32 s28, s8, s26
	v_add_u32_e32 v140, s45, v145
	s_cselect_b32 s27, s17, s43
	s_cselect_b32 s26, s19, s35
	s_add_i32 s47, 0, 0x14000
	ds_read_b128 v[150:153], v140
	ds_read_b128 v[154:157], v140 offset:1024
	ds_read_b128 v[158:161], v140 offset:2048
	ds_read_b128 v[162:165], v140 offset:3072
	v_add_u32_e32 v140, s47, v145
	ds_read_b128 v[166:169], v140
	ds_read_b128 v[170:173], v140 offset:1024
	ds_read_b128 v[174:177], v140 offset:2048
	ds_read_b128 v[178:181], v140 offset:3072
	v_lshl_add_u64 v[140:141], s[24:25], 0, v[136:137]
	s_add_i32 m0, s30, 0xc000
	ds_read_b128 v[182:185], v149
	ds_read_b128 v[194:197], v149 offset:1024
	ds_read_b128 v[198:201], v149 offset:2048
	ds_read_b128 v[202:205], v149 offset:3072
	ds_read_b128 v[206:209], v149 offset:4096
	ds_read_b128 v[210:213], v149 offset:5120
	ds_read_b128 v[214:217], v149 offset:6144
	ds_read_b128 v[218:221], v149 offset:7168
	global_load_lds_dwordx4 v[140:141], off
	v_lshl_add_u64 v[140:141], s[24:25], 0, v[138:139]
	s_add_i32 m0, s30, 0xe000
	s_nop 0
	global_load_lds_dwordx4 v[140:141], off
	s_waitcnt vmcnt(8)
	s_waitcnt lgkmcnt(0)
	s_barrier
	s_setprio 1
	s_waitcnt lgkmcnt(0)
	v_mfma_f32_16x16x32_bf16 v[126:129], v[150:153], v[182:185], v[126:129]
	v_mfma_f32_16x16x32_bf16 v[122:125], v[158:161], v[182:185], v[122:125]
	v_mfma_f32_16x16x32_bf16 v[106:109], v[158:161], v[198:201], v[106:109]
	v_mfma_f32_16x16x32_bf16 v[110:113], v[150:153], v[198:201], v[110:113]
	v_mfma_f32_16x16x32_bf16 v[94:97], v[150:153], v[206:209], v[94:97]
	v_mfma_f32_16x16x32_bf16 v[90:93], v[158:161], v[206:209], v[90:93]
	v_mfma_f32_16x16x32_bf16 v[74:77], v[158:161], v[214:217], v[74:77]
	v_mfma_f32_16x16x32_bf16 v[78:81], v[150:153], v[214:217], v[78:81]
	v_mfma_f32_16x16x32_bf16 v[126:129], v[154:157], v[194:197], v[126:129]
	v_mfma_f32_16x16x32_bf16 v[122:125], v[162:165], v[194:197], v[122:125]
	v_mfma_f32_16x16x32_bf16 v[106:109], v[162:165], v[202:205], v[106:109]
	v_mfma_f32_16x16x32_bf16 v[110:113], v[154:157], v[202:205], v[110:113]
	v_mfma_f32_16x16x32_bf16 v[94:97], v[154:157], v[210:213], v[94:97]
	v_mfma_f32_16x16x32_bf16 v[90:93], v[162:165], v[210:213], v[90:93]
	v_mfma_f32_16x16x32_bf16 v[74:77], v[162:165], v[218:221], v[74:77]
	v_mfma_f32_16x16x32_bf16 v[78:81], v[154:157], v[218:221], v[78:81]
	s_setprio 0
	s_setprio 1
	v_mfma_f32_16x16x32_bf16 v[118:121], v[166:169], v[182:185], v[118:121]
	v_mfma_f32_16x16x32_bf16 v[114:117], v[174:177], v[182:185], v[114:117]
	v_mfma_f32_16x16x32_bf16 v[98:101], v[174:177], v[198:201], v[98:101]
	v_mfma_f32_16x16x32_bf16 v[102:105], v[166:169], v[198:201], v[102:105]
	v_mfma_f32_16x16x32_bf16 v[86:89], v[166:169], v[206:209], v[86:89]
	v_mfma_f32_16x16x32_bf16 v[82:85], v[174:177], v[206:209], v[82:85]
	v_mfma_f32_16x16x32_bf16 v[66:69], v[174:177], v[214:217], v[66:69]
	v_mfma_f32_16x16x32_bf16 v[70:73], v[166:169], v[214:217], v[70:73]
	v_mfma_f32_16x16x32_bf16 v[118:121], v[170:173], v[194:197], v[118:121]
	v_mfma_f32_16x16x32_bf16 v[114:117], v[178:181], v[194:197], v[114:117]
	v_mfma_f32_16x16x32_bf16 v[98:101], v[178:181], v[202:205], v[98:101]
	v_mfma_f32_16x16x32_bf16 v[102:105], v[170:173], v[202:205], v[102:105]
	v_mfma_f32_16x16x32_bf16 v[86:89], v[170:173], v[210:213], v[86:89]
	v_mfma_f32_16x16x32_bf16 v[82:85], v[178:181], v[210:213], v[82:85]
	v_mfma_f32_16x16x32_bf16 v[66:69], v[178:181], v[218:221], v[66:69]
	v_mfma_f32_16x16x32_bf16 v[70:73], v[170:173], v[218:221], v[70:73]
	s_setprio 0
	s_barrier
	s_add_i32 s45, s45, s9
	v_lshl_add_u64 v[140:141], s[26:27], 0, v[0:1]
	s_mov_b32 m0, s45
	ds_read_b128 v[182:185], v149 offset:16384
	ds_read_b128 v[194:197], v149 offset:17408
	ds_read_b128 v[198:201], v149 offset:18432
	ds_read_b128 v[202:205], v149 offset:19456
	ds_read_b128 v[206:209], v149 offset:20480
	ds_read_b128 v[210:213], v149 offset:21504
	ds_read_b128 v[214:217], v149 offset:22528
	ds_read_b128 v[218:221], v149 offset:23552
	global_load_lds_dwordx4 v[140:141], off
	s_add_i32 m0, s45, 0x2000
	s_add_u32 s48, s26, 0x80000
	v_lshl_add_u64 v[186:187], s[26:27], 0, v[130:131]
	s_addc_u32 s49, s27, 0
	s_add_i32 s45, s47, s9
	global_load_lds_dwordx4 v[186:187], off
	v_lshl_add_u64 v[188:189], s[48:49], 0, v[0:1]
	s_mov_b32 m0, s45
	v_lshl_add_u64 v[190:191], s[28:29], 0, v[132:133]
	global_load_lds_dwordx4 v[188:189], off
	v_lshl_add_u64 v[188:189], s[48:49], 0, v[130:131]
	s_add_i32 m0, s45, 0x2000
	s_nop 0
	global_load_lds_dwordx4 v[188:189], off
	v_lshl_add_u64 v[188:189], s[28:29], 0, v[134:135]
	s_mov_b32 m0, s30
	s_nop 0
	global_load_lds_dwordx4 v[188:189], off
	s_mov_b32 m0, s31
	s_nop 0
	global_load_lds_dwordx4 v[190:191], off
	s_waitcnt vmcnt(8)
	s_waitcnt lgkmcnt(0)
	s_barrier
; #define PG8_STAGE(bufoff, gbase, voff) do { _Pragma("unroll") for (int _i = 0; _i < 2; ++_i) \
;         __builtin_amdgcn_global_load_lds((const unsigned*)((const char*)(gbase) + (voff)[_i]), (LAS unsigned*)(lds + (bufoff) + ldsw + _i * 8192), 16, 0, 0); } while (0)
; #define PG8_LDA(dst, b, h) do { _Pragma("unroll") for (int m = 0; m < 4; ++m) _Pragma("unroll") for (int k = 0; k < 2; ++k) dst[m][k] = *(const LAS bf16x8*)(lds + PG8_SA(b, h) + aoff + m * 2048 + k * 1024); } while (0)
; #define PG8_LDB(dst, b, h) do { _Pragma("unroll") for (int n = 0; n < 2; ++n) _Pragma("unroll") for (int k = 0; k < 2; ++k) dst[n][k] = *(const LAS bf16x8*)(lds + PG8_SB(b, h) + boff + n * 2048 + k * 1024); } while (0)
; #define PG8_MMA(ai, bj, At, Bt) do { __builtin_amdgcn_s_setprio(1); _Pragma("unroll") for (int m = 0; m < 4; ++m) _Pragma("unroll") for (int n = 0; n < 2; ++n) _Pragma("unroll") for (int k = 0; k < 2; ++k) \
;         acc[ai][bj][m][n] = __builtin_amdgcn_mfma_f32_16x16x32_bf16(Bt[n][k], At[m][k], acc[ai][bj][m][n], 0, 0, 0); __builtin_amdgcn_s_setprio(0); } while (0)
; #define PG8_WAIT_V(n) asm volatile("s_waitcnt vmcnt(" #n ")" ::: "memory")
; #define PG8_WAIT_L(n) asm volatile("s_waitcnt lgkmcnt(" #n ")" ::: "memory")
; #define PG8_BAR __builtin_amdgcn_s_barrier()
; #define PG8_SCHED __builtin_amdgcn_sched_barrier(0)
; template <class Epi, class Sched, bool ALIGN_EPI = false, bool SP2 = false>
; __device__ __forceinline__ void gemm_phase(LAS unsigned char* lds, const Gemm g, const Sched& S, const Epi& E) {
;     ...
;             PG8_WAIT_V(8); PG8_WAIT_L(0); PG8_BAR; PG8_MMA(1, 0, At, B0); PG8_MMA(1, 1, At, B1); PG8_BAR; PG8_SCHED;
;             PG8_LDB(B0, 1, 0); PG8_LDB(B1, 1, 1); PG8_SCHED; PG8_LDA(At, 1, 0); PG8_STAGE(PG8_SA(0, 1), a2 + hstep, voffA);
;             PG8_WAIT_V(8); PG8_WAIT_L(0); PG8_BAR; PG8_MMA(0, 0, At, B0); PG8_MMA(0, 1, At, B1); PG8_BAR; PG8_SCHED;
;             PG8_LDA(At, 1, 1); PG8_STAGE(PG8_SB(1, 0), b3, voffB); PG8_STAGE(PG8_SB(1, 1), b3 + hstep, voffB); PG8_STAGE(PG8_SA(1, 0), a3, voffA);
	s_setprio 1
	s_waitcnt lgkmcnt(0)
	v_mfma_f32_16x16x32_bf16 v[62:65], v[150:153], v[182:185], v[62:65]
	v_mfma_f32_16x16x32_bf16 v[58:61], v[158:161], v[182:185], v[58:61]
	v_mfma_f32_16x16x32_bf16 v[42:45], v[158:161], v[198:201], v[42:45]
	v_mfma_f32_16x16x32_bf16 v[46:49], v[150:153], v[198:201], v[46:49]
	v_mfma_f32_16x16x32_bf16 v[30:33], v[150:153], v[206:209], v[30:33]
	v_mfma_f32_16x16x32_bf16 v[26:29], v[158:161], v[206:209], v[26:29]
	v_mfma_f32_16x16x32_bf16 v[10:13], v[158:161], v[214:217], v[10:13]
	v_mfma_f32_16x16x32_bf16 v[14:17], v[150:153], v[214:217], v[14:17]
	v_mfma_f32_16x16x32_bf16 v[62:65], v[154:157], v[194:197], v[62:65]
	v_mfma_f32_16x16x32_bf16 v[58:61], v[162:165], v[194:197], v[58:61]
	v_mfma_f32_16x16x32_bf16 v[42:45], v[162:165], v[202:205], v[42:45]
	v_mfma_f32_16x16x32_bf16 v[46:49], v[154:157], v[202:205], v[46:49]
	v_mfma_f32_16x16x32_bf16 v[30:33], v[154:157], v[210:213], v[30:33]
	v_mfma_f32_16x16x32_bf16 v[26:29], v[162:165], v[210:213], v[26:29]
	v_mfma_f32_16x16x32_bf16 v[10:13], v[162:165], v[218:221], v[10:13]
	v_mfma_f32_16x16x32_bf16 v[14:17], v[154:157], v[218:221], v[14:17]
	s_setprio 0
	s_setprio 1
	v_mfma_f32_16x16x32_bf16 v[54:57], v[166:169], v[182:185], v[54:57]
	v_mfma_f32_16x16x32_bf16 v[50:53], v[174:177], v[182:185], v[50:53]
	v_mfma_f32_16x16x32_bf16 v[34:37], v[174:177], v[198:201], v[34:37]
	v_mfma_f32_16x16x32_bf16 v[38:41], v[166:169], v[198:201], v[38:41]
	v_mfma_f32_16x16x32_bf16 v[22:25], v[166:169], v[206:209], v[22:25]
	v_mfma_f32_16x16x32_bf16 v[18:21], v[174:177], v[206:209], v[18:21]
	v_mfma_f32_16x16x32_bf16 v[2:5], v[174:177], v[214:217], v[2:5]
	v_mfma_f32_16x16x32_bf16 v[6:9], v[166:169], v[214:217], v[6:9]
	v_mfma_f32_16x16x32_bf16 v[54:57], v[170:173], v[194:197], v[54:57]
	v_mfma_f32_16x16x32_bf16 v[50:53], v[178:181], v[194:197], v[50:53]
	v_mfma_f32_16x16x32_bf16 v[34:37], v[178:181], v[202:205], v[34:37]
	v_mfma_f32_16x16x32_bf16 v[38:41], v[170:173], v[202:205], v[38:41]
	v_mfma_f32_16x16x32_bf16 v[22:25], v[170:173], v[210:213], v[22:25]
	v_mfma_f32_16x16x32_bf16 v[18:21], v[178:181], v[210:213], v[18:21]
	v_mfma_f32_16x16x32_bf16 v[2:5], v[178:181], v[218:221], v[2:5]
	v_mfma_f32_16x16x32_bf16 v[6:9], v[170:173], v[218:221], v[6:9]
	s_setprio 0
	s_barrier
	s_add_i32 s45, 0, 0x18000
	v_add_u32_e32 v142, s45, v145
	s_add_i32 s47, 0, 0x1c000
	ds_read_b128 v[150:153], v142
	ds_read_b128 v[154:157], v142 offset:1024
	ds_read_b128 v[158:161], v142 offset:2048
	ds_read_b128 v[162:165], v142 offset:3072
	v_add_u32_e32 v142, s47, v145
	ds_read_b128 v[166:169], v142
	ds_read_b128 v[170:173], v142 offset:1024
	ds_read_b128 v[174:177], v142 offset:2048
	ds_read_b128 v[178:181], v142 offset:3072
	s_add_u32 s28, s28, 0x80000
	s_addc_u32 s29, s29, 0
	s_mov_b32 m0, s38
	v_lshl_add_u64 v[192:193], s[28:29], 0, v[134:135]
	ds_read_b128 v[182:185], v149 offset:32768
	ds_read_b128 v[194:197], v149 offset:33792
	ds_read_b128 v[198:201], v149 offset:34816
	ds_read_b128 v[202:205], v149 offset:35840
	ds_read_b128 v[206:209], v149 offset:36864
	ds_read_b128 v[210:213], v149 offset:37888
	ds_read_b128 v[214:217], v149 offset:38912
	ds_read_b128 v[218:221], v149 offset:39936
	global_load_lds_dwordx4 v[192:193], off
	v_lshl_add_u64 v[192:193], s[28:29], 0, v[132:133]
	s_mov_b32 m0, s39
	s_nop 0
	global_load_lds_dwordx4 v[192:193], off
	s_waitcnt vmcnt(8)
	s_waitcnt lgkmcnt(0)
	s_barrier
	s_setprio 1
	s_waitcnt lgkmcnt(0)
	v_mfma_f32_16x16x32_bf16 v[126:129], v[150:153], v[182:185], v[126:129]
	v_mfma_f32_16x16x32_bf16 v[122:125], v[158:161], v[182:185], v[122:125]
	v_mfma_f32_16x16x32_bf16 v[106:109], v[158:161], v[198:201], v[106:109]
	v_mfma_f32_16x16x32_bf16 v[110:113], v[150:153], v[198:201], v[110:113]
	v_mfma_f32_16x16x32_bf16 v[94:97], v[150:153], v[206:209], v[94:97]
	v_mfma_f32_16x16x32_bf16 v[90:93], v[158:161], v[206:209], v[90:93]
	v_mfma_f32_16x16x32_bf16 v[74:77], v[158:161], v[214:217], v[74:77]
	v_mfma_f32_16x16x32_bf16 v[78:81], v[150:153], v[214:217], v[78:81]
	v_mfma_f32_16x16x32_bf16 v[126:129], v[154:157], v[194:197], v[126:129]
	v_mfma_f32_16x16x32_bf16 v[122:125], v[162:165], v[194:197], v[122:125]
	v_mfma_f32_16x16x32_bf16 v[106:109], v[162:165], v[202:205], v[106:109]
	v_mfma_f32_16x16x32_bf16 v[110:113], v[154:157], v[202:205], v[110:113]
	v_mfma_f32_16x16x32_bf16 v[94:97], v[154:157], v[210:213], v[94:97]
	v_mfma_f32_16x16x32_bf16 v[90:93], v[162:165], v[210:213], v[90:93]
	v_mfma_f32_16x16x32_bf16 v[74:77], v[162:165], v[218:221], v[74:77]
	v_mfma_f32_16x16x32_bf16 v[78:81], v[154:157], v[218:221], v[78:81]
	s_setprio 0
	s_setprio 1
	v_mfma_f32_16x16x32_bf16 v[118:121], v[166:169], v[182:185], v[118:121]
	v_mfma_f32_16x16x32_bf16 v[114:117], v[174:177], v[182:185], v[114:117]
	v_mfma_f32_16x16x32_bf16 v[98:101], v[174:177], v[198:201], v[98:101]
	v_mfma_f32_16x16x32_bf16 v[102:105], v[166:169], v[198:201], v[102:105]
	v_mfma_f32_16x16x32_bf16 v[86:89], v[166:169], v[206:209], v[86:89]
	v_mfma_f32_16x16x32_bf16 v[82:85], v[174:177], v[206:209], v[82:85]
	v_mfma_f32_16x16x32_bf16 v[66:69], v[174:177], v[214:217], v[66:69]
	v_mfma_f32_16x16x32_bf16 v[70:73], v[166:169], v[214:217], v[70:73]
	v_mfma_f32_16x16x32_bf16 v[118:121], v[170:173], v[194:197], v[118:121]
	v_mfma_f32_16x16x32_bf16 v[114:117], v[178:181], v[194:197], v[114:117]
	v_mfma_f32_16x16x32_bf16 v[98:101], v[178:181], v[202:205], v[98:101]
	v_mfma_f32_16x16x32_bf16 v[102:105], v[170:173], v[202:205], v[102:105]
	v_mfma_f32_16x16x32_bf16 v[86:89], v[170:173], v[210:213], v[86:89]
	v_mfma_f32_16x16x32_bf16 v[82:85], v[178:181], v[210:213], v[82:85]
	v_mfma_f32_16x16x32_bf16 v[66:69], v[178:181], v[218:221], v[66:69]
	v_mfma_f32_16x16x32_bf16 v[70:73], v[170:173], v[218:221], v[70:73]
	s_setprio 0
	s_barrier
; #define PG8_STAGE(bufoff, gbase, voff) do { _Pragma("unroll") for (int _i = 0; _i < 2; ++_i) \
;         __builtin_amdgcn_global_load_lds((const unsigned*)((const char*)(gbase) + (voff)[_i]), (LAS unsigned*)(lds + (bufoff) + ldsw + _i * 8192), 16, 0, 0); } while (0)
; #define PG8_LDA(dst, b, h) do { _Pragma("unroll") for (int m = 0; m < 4; ++m) _Pragma("unroll") for (int k = 0; k < 2; ++k) dst[m][k] = *(const LAS bf16x8*)(lds + PG8_SA(b, h) + aoff + m * 2048 + k * 1024); } while (0)
; #define PG8_MMA(ai, bj, At, Bt) do { __builtin_amdgcn_s_setprio(1); _Pragma("unroll") for (int m = 0; m < 4; ++m) _Pragma("unroll") for (int n = 0; n < 2; ++n) _Pragma("unroll") for (int k = 0; k < 2; ++k) \
;         acc[ai][bj][m][n] = __builtin_amdgcn_mfma_f32_16x16x32_bf16(Bt[n][k], At[m][k], acc[ai][bj][m][n], 0, 0, 0); __builtin_amdgcn_s_setprio(0); } while (0)
; #define PG8_WAIT_V(n) asm volatile("s_waitcnt vmcnt(" #n ")" ::: "memory")
; #define PG8_WAIT_L(n) asm volatile("s_waitcnt lgkmcnt(" #n ")" ::: "memory")
; #define PG8_BAR __builtin_amdgcn_s_barrier()
; #define PG8_SCHED __builtin_amdgcn_sched_barrier(0)
; template <class Epi, class Sched, bool ALIGN_EPI = false, bool SP2 = false>
; __device__ __forceinline__ void gemm_phase(LAS unsigned char* lds, const Gemm g, const Sched& S, const Epi& E) {
;     ...
;             PG8_LDA(At, 1, 1); PG8_STAGE(PG8_SB(1, 0), b3, voffB); PG8_STAGE(PG8_SB(1, 1), b3 + hstep, voffB); PG8_STAGE(PG8_SA(1, 0), a3, voffA);
;             PG8_WAIT_V(8); PG8_WAIT_L(0); PG8_BAR; PG8_MMA(1, 0, At, B0); PG8_MMA(1, 1, At, B1); PG8_BAR; PG8_SCHED;
;     ...
;         if constexpr (ALIGN_EPI) { if (wr == 0) PG8_BAR; }
	s_add_i32 s28, s45, s9
	v_lshl_add_u64 v[140:141], v[140:141], 0, s[12:13]
	s_mov_b32 m0, s28
	ds_read_b128 v[182:185], v149 offset:49152
	ds_read_b128 v[194:197], v149 offset:50176
	ds_read_b128 v[198:201], v149 offset:51200
	ds_read_b128 v[202:205], v149 offset:52224
	ds_read_b128 v[206:209], v149 offset:53248
	ds_read_b128 v[210:213], v149 offset:54272
	ds_read_b128 v[214:217], v149 offset:55296
	ds_read_b128 v[218:221], v149 offset:56320
	global_load_lds_dwordx4 v[140:141], off
	s_add_i32 m0, s28, 0x2000
	s_add_u32 s26, s26, 0x80080
	v_lshl_add_u64 v[140:141], v[186:187], 0, s[12:13]
	s_addc_u32 s27, s27, 0
	s_add_i32 s28, s47, s9
	global_load_lds_dwordx4 v[140:141], off
	v_lshl_add_u64 v[140:141], s[26:27], 0, v[0:1]
	s_mov_b32 m0, s28
	s_nop 0
	global_load_lds_dwordx4 v[140:141], off
	v_lshl_add_u64 v[140:141], s[26:27], 0, v[130:131]
	s_add_i32 m0, s28, 0x2000
	s_nop 0
	global_load_lds_dwordx4 v[140:141], off
	v_lshl_add_u64 v[140:141], v[188:189], 0, s[12:13]
	s_mov_b32 m0, s40
	s_nop 0
	global_load_lds_dwordx4 v[140:141], off
	v_lshl_add_u64 v[140:141], v[190:191], 0, s[12:13]
	s_mov_b32 m0, s41
	s_nop 0
	global_load_lds_dwordx4 v[140:141], off
	s_waitcnt vmcnt(8)
	s_waitcnt lgkmcnt(0)
	s_barrier
	s_setprio 1
	s_waitcnt lgkmcnt(0)
	v_mfma_f32_16x16x32_bf16 v[62:65], v[150:153], v[182:185], v[62:65]
	v_mfma_f32_16x16x32_bf16 v[58:61], v[158:161], v[182:185], v[58:61]
	v_mfma_f32_16x16x32_bf16 v[42:45], v[158:161], v[198:201], v[42:45]
	v_mfma_f32_16x16x32_bf16 v[46:49], v[150:153], v[198:201], v[46:49]
	v_mfma_f32_16x16x32_bf16 v[30:33], v[150:153], v[206:209], v[30:33]
	v_mfma_f32_16x16x32_bf16 v[26:29], v[158:161], v[206:209], v[26:29]
	v_mfma_f32_16x16x32_bf16 v[10:13], v[158:161], v[214:217], v[10:13]
	v_mfma_f32_16x16x32_bf16 v[14:17], v[150:153], v[214:217], v[14:17]
	v_mfma_f32_16x16x32_bf16 v[62:65], v[154:157], v[194:197], v[62:65]
	v_mfma_f32_16x16x32_bf16 v[58:61], v[162:165], v[194:197], v[58:61]
	v_mfma_f32_16x16x32_bf16 v[42:45], v[162:165], v[202:205], v[42:45]
	v_mfma_f32_16x16x32_bf16 v[46:49], v[154:157], v[202:205], v[46:49]
	v_mfma_f32_16x16x32_bf16 v[30:33], v[154:157], v[210:213], v[30:33]
	v_mfma_f32_16x16x32_bf16 v[26:29], v[162:165], v[210:213], v[26:29]
	v_mfma_f32_16x16x32_bf16 v[10:13], v[162:165], v[218:221], v[10:13]
	v_mfma_f32_16x16x32_bf16 v[14:17], v[154:157], v[218:221], v[14:17]
	s_setprio 0
	s_setprio 1
	v_mfma_f32_16x16x32_bf16 v[54:57], v[166:169], v[182:185], v[54:57]
	v_mfma_f32_16x16x32_bf16 v[50:53], v[174:177], v[182:185], v[50:53]
	v_mfma_f32_16x16x32_bf16 v[34:37], v[174:177], v[198:201], v[34:37]
	v_mfma_f32_16x16x32_bf16 v[38:41], v[166:169], v[198:201], v[38:41]
	v_mfma_f32_16x16x32_bf16 v[22:25], v[166:169], v[206:209], v[22:25]
	v_mfma_f32_16x16x32_bf16 v[18:21], v[174:177], v[206:209], v[18:21]
	v_mfma_f32_16x16x32_bf16 v[2:5], v[174:177], v[214:217], v[2:5]
	v_mfma_f32_16x16x32_bf16 v[6:9], v[166:169], v[214:217], v[6:9]
	v_mfma_f32_16x16x32_bf16 v[54:57], v[170:173], v[194:197], v[54:57]
	v_mfma_f32_16x16x32_bf16 v[50:53], v[178:181], v[194:197], v[50:53]
	v_mfma_f32_16x16x32_bf16 v[34:37], v[178:181], v[202:205], v[34:37]
	v_mfma_f32_16x16x32_bf16 v[38:41], v[170:173], v[202:205], v[38:41]
	v_mfma_f32_16x16x32_bf16 v[22:25], v[170:173], v[210:213], v[22:25]
	v_mfma_f32_16x16x32_bf16 v[18:21], v[178:181], v[210:213], v[18:21]
	v_mfma_f32_16x16x32_bf16 v[2:5], v[178:181], v[218:221], v[2:5]
	v_mfma_f32_16x16x32_bf16 v[6:9], v[170:173], v[218:221], v[6:9]
	s_setprio 0
	s_barrier
	s_add_i32 s44, s44, 2
	s_add_u32 s24, s24, 0x100
	s_addc_u32 s25, s25, 0
	s_add_u32 s35, s35, 0x100
	s_addc_u32 s43, s43, 0
	s_cmp_gt_u32 s44, 29
	s_cbranch_scc0 .LBB0_173
	s_and_b64 vcc, exec, s[4:5]
	s_cbranch_vccz .LBB0_176
	s_barrier

; #define PG8_STAGE(bufoff, gbase, voff) do { _Pragma("unroll") for (int _i = 0; _i < 2; ++_i) \
;         __builtin_amdgcn_global_load_lds((const unsigned*)((const char*)(gbase) + (voff)[_i]), (LAS unsigned*)(lds + (bufoff) + ldsw + _i * 8192), 16, 0, 0); } while (0)
; #define PG8_LDA(dst, b, h) do { _Pragma("unroll") for (int m = 0; m < 4; ++m) _Pragma("unroll") for (int k = 0; k < 2; ++k) dst[m][k] = *(const LAS bf16x8*)(lds + PG8_SA(b, h) + aoff + m * 2048 + k * 1024); } while (0)
; #define PG8_LDB(dst, b, h) do { _Pragma("unroll") for (int n = 0; n < 2; ++n) _Pragma("unroll") for (int k = 0; k < 2; ++k) dst[n][k] = *(const LAS bf16x8*)(lds + PG8_SB(b, h) + boff + n * 2048 + k * 1024); } while (0)
; #define PG8_MMA(ai, bj, At, Bt) do { __builtin_amdgcn_s_setprio(1); _Pragma("unroll") for (int m = 0; m < 4; ++m) _Pragma("unroll") for (int n = 0; n < 2; ++n) _Pragma("unroll") for (int k = 0; k < 2; ++k) \
;         acc[ai][bj][m][n] = __builtin_amdgcn_mfma_f32_16x16x32_bf16(Bt[n][k], At[m][k], acc[ai][bj][m][n], 0, 0, 0); __builtin_amdgcn_s_setprio(0); } while (0)
; #define PG8_WAIT_V(n) asm volatile("s_waitcnt vmcnt(" #n ")" ::: "memory")
; #define PG8_WAIT_L(n) asm volatile("s_waitcnt lgkmcnt(" #n ")" ::: "memory")
; template <class Epi, class Sched, bool ALIGN_EPI = false, bool SP2 = false>
; __device__ __forceinline__ void gemm_phase(LAS unsigned char* lds, const Gemm g, const Sched& S, const Epi& E) {
;     ...
;         for (int t = 0; t < nt; t += 2) {
;             const bool last = (t == nt - 2);
;             const char* a1 = cA + (size_t)(t + 1) * kstep;
;             const char* a2 = last ? nA : cA + (size_t)(t + 2) * kstep; const char* b2 = last ? nB : cB + (size_t)(t + 2) * kstep;
;             const char* a3 = a2 + kstep; const char* b3 = b2 + kstep;
;             if (last && has_next) S.a_ready(nxt);
;             if constexpr (SP2) {
;             PG8_LDB(B0, 0, 0); PG8_LDB(B1, 0, 1); PG8_SCHED; PG8_LDA(At, 0, 0); PG8_STAGE(PG8_SA(1, 1), a1 + hstep, voffA);
;             PG8_WAIT_V(8); PG8_WAIT_L(0); PG8_BAR; PG8_MMA(0, 0, At, B0); PG8_MMA(0, 1, At, B1); PG8_BAR; PG8_SCHED;
;             PG8_LDA(At, 0, 1); PG8_STAGE(PG8_SB(0, 0), b2, voffB); PG8_STAGE(PG8_SB(0, 1), b2 + hstep, voffB); PG8_STAGE(PG8_SA(0, 0), a2, voffA);
;             PG8_WAIT_V(8); PG8_WAIT_L(0); PG8_BAR; PG8_MMA(1, 0, At, B0); PG8_MMA(1, 1, At, B1); PG8_BAR; PG8_SCHED;
.LBB0_257:
	s_add_u32 s24, s22, 0x100
	s_addc_u32 s25, s23, 0
	s_add_i32 s50, 0, 0x10000
	s_cmpk_eq_i32 s49, 0x54
	s_cselect_b32 s29, s1, s25
	s_cselect_b32 s28, s0, s24
	s_cselect_b32 s27, s21, s48
	s_cselect_b32 s26, s20, s47
	s_add_i32 s51, 0, 0x14000
	v_add_u32_e32 v126, s50, v247
	v_add_u32_e32 v158, s51, v247
	ds_read_b128 v[90:93], v126
	ds_read_b128 v[102:105], v126 offset:1024
	ds_read_b128 v[114:117], v126 offset:2048
	ds_read_b128 v[126:129], v126 offset:3072
	ds_read_b128 v[138:141], v158
	ds_read_b128 v[142:145], v158 offset:1024
	ds_read_b128 v[154:157], v158 offset:2048
	ds_read_b128 v[158:161], v158 offset:3072
	v_lshl_add_u64 v[186:187], s[22:23], 0, v[200:201]
	s_add_i32 m0, s6, 0xc000
	ds_read_b128 v[162:165], v249
	ds_read_b128 v[166:169], v249 offset:1024
	ds_read_b128 v[170:173], v249 offset:2048
	ds_read_b128 v[174:177], v249 offset:3072
	ds_read_b128 v[178:181], v249 offset:4096
	ds_read_b128 v[182:185], v249 offset:5120
	ds_read_b128 v[204:207], v249 offset:6144
	ds_read_b128 v[208:211], v249 offset:7168
	global_load_lds_dwordx4 v[186:187], off
	v_lshl_add_u64 v[186:187], s[22:23], 0, v[202:203]
	s_add_i32 m0, s6, 0xe000
	s_nop 0
	global_load_lds_dwordx4 v[186:187], off
	s_waitcnt vmcnt(8)
	s_waitcnt lgkmcnt(0)
	s_barrier
	s_setprio 1
	s_waitcnt lgkmcnt(0)
	v_mfma_f32_16x16x32_bf16 v[150:153], v[90:93], v[162:165], v[150:153]
	v_mfma_f32_16x16x32_bf16 v[146:149], v[114:117], v[162:165], v[146:149]
	v_mfma_f32_16x16x32_bf16 v[118:121], v[114:117], v[170:173], v[118:121]
	v_mfma_f32_16x16x32_bf16 v[122:125], v[90:93], v[170:173], v[122:125]
	v_mfma_f32_16x16x32_bf16 v[98:101], v[90:93], v[178:181], v[98:101]
	v_mfma_f32_16x16x32_bf16 v[94:97], v[114:117], v[178:181], v[94:97]
	v_mfma_f32_16x16x32_bf16 v[74:77], v[114:117], v[204:207], v[74:77]
	v_mfma_f32_16x16x32_bf16 v[78:81], v[90:93], v[204:207], v[78:81]
	v_mfma_f32_16x16x32_bf16 v[150:153], v[102:105], v[166:169], v[150:153]
	v_mfma_f32_16x16x32_bf16 v[146:149], v[126:129], v[166:169], v[146:149]
	v_mfma_f32_16x16x32_bf16 v[118:121], v[126:129], v[174:177], v[118:121]
	v_mfma_f32_16x16x32_bf16 v[122:125], v[102:105], v[174:177], v[122:125]
	v_mfma_f32_16x16x32_bf16 v[98:101], v[102:105], v[182:185], v[98:101]
	v_mfma_f32_16x16x32_bf16 v[94:97], v[126:129], v[182:185], v[94:97]
	v_mfma_f32_16x16x32_bf16 v[74:77], v[126:129], v[208:211], v[74:77]
	v_mfma_f32_16x16x32_bf16 v[78:81], v[102:105], v[208:211], v[78:81]
	s_setprio 0
	s_setprio 1
	v_mfma_f32_16x16x32_bf16 v[134:137], v[138:141], v[162:165], v[134:137]
	v_mfma_f32_16x16x32_bf16 v[130:133], v[154:157], v[162:165], v[130:133]
	v_mfma_f32_16x16x32_bf16 v[106:109], v[154:157], v[170:173], v[106:109]
	v_mfma_f32_16x16x32_bf16 v[110:113], v[138:141], v[170:173], v[110:113]
	v_mfma_f32_16x16x32_bf16 v[86:89], v[138:141], v[178:181], v[86:89]
	v_mfma_f32_16x16x32_bf16 v[82:85], v[154:157], v[178:181], v[82:85]
	v_mfma_f32_16x16x32_bf16 v[66:69], v[154:157], v[204:207], v[66:69]
	v_mfma_f32_16x16x32_bf16 v[70:73], v[138:141], v[204:207], v[70:73]
	v_mfma_f32_16x16x32_bf16 v[134:137], v[142:145], v[166:169], v[134:137]
	v_mfma_f32_16x16x32_bf16 v[130:133], v[158:161], v[166:169], v[130:133]
	v_mfma_f32_16x16x32_bf16 v[106:109], v[158:161], v[174:177], v[106:109]
	v_mfma_f32_16x16x32_bf16 v[110:113], v[142:145], v[174:177], v[110:113]
	v_mfma_f32_16x16x32_bf16 v[86:89], v[142:145], v[182:185], v[86:89]
	v_mfma_f32_16x16x32_bf16 v[82:85], v[158:161], v[182:185], v[82:85]
	v_mfma_f32_16x16x32_bf16 v[66:69], v[158:161], v[208:211], v[66:69]
	v_mfma_f32_16x16x32_bf16 v[70:73], v[142:145], v[208:211], v[70:73]
	s_setprio 0
	s_barrier
	s_add_i32 s22, s50, s2
	v_lshl_add_u64 v[186:187], s[26:27], 0, v[0:1]
	s_mov_b32 m0, s22
	ds_read_b128 v[162:165], v249 offset:16384
	ds_read_b128 v[166:169], v249 offset:17408
	ds_read_b128 v[170:173], v249 offset:18432
	ds_read_b128 v[174:177], v249 offset:19456
	ds_read_b128 v[178:181], v249 offset:20480
	ds_read_b128 v[182:185], v249 offset:21504
	ds_read_b128 v[204:207], v249 offset:22528
	ds_read_b128 v[208:211], v249 offset:23552
	global_load_lds_dwordx4 v[186:187], off
	s_add_i32 m0, s22, 0x2000
	s_add_u32 s22, s26, 0x160000
	v_lshl_add_u64 v[188:189], s[26:27], 0, v[194:195]
	s_addc_u32 s23, s27, 0
	s_add_i32 s50, s51, s2
	global_load_lds_dwordx4 v[188:189], off
	v_lshl_add_u64 v[190:191], s[22:23], 0, v[0:1]
	s_mov_b32 m0, s50
	v_lshl_add_u64 v[192:193], s[28:29], 0, v[196:197]
	global_load_lds_dwordx4 v[190:191], off
	v_lshl_add_u64 v[190:191], s[22:23], 0, v[194:195]
	s_add_i32 m0, s50, 0x2000
	s_nop 0
	global_load_lds_dwordx4 v[190:191], off
	v_lshl_add_u64 v[190:191], s[28:29], 0, v[198:199]
	s_mov_b32 m0, s6
	s_nop 0
	global_load_lds_dwordx4 v[190:191], off
	s_mov_b32 m0, s7
	s_nop 0
	global_load_lds_dwordx4 v[192:193], off
	s_waitcnt vmcnt(8)
	s_waitcnt lgkmcnt(0)
	s_barrier
; #define PG8_STAGE(bufoff, gbase, voff) do { _Pragma("unroll") for (int _i = 0; _i < 2; ++_i) \
;         __builtin_amdgcn_global_load_lds((const unsigned*)((const char*)(gbase) + (voff)[_i]), (LAS unsigned*)(lds + (bufoff) + ldsw + _i * 8192), 16, 0, 0); } while (0)
; #define PG8_LDA(dst, b, h) do { _Pragma("unroll") for (int m = 0; m < 4; ++m) _Pragma("unroll") for (int k = 0; k < 2; ++k) dst[m][k] = *(const LAS bf16x8*)(lds + PG8_SA(b, h) + aoff + m * 2048 + k * 1024); } while (0)
; #define PG8_LDB(dst, b, h) do { _Pragma("unroll") for (int n = 0; n < 2; ++n) _Pragma("unroll") for (int k = 0; k < 2; ++k) dst[n][k] = *(const LAS bf16x8*)(lds + PG8_SB(b, h) + boff + n * 2048 + k * 1024); } while (0)
; #define PG8_MMA(ai, bj, At, Bt) do { __builtin_amdgcn_s_setprio(1); _Pragma("unroll") for (int m = 0; m < 4; ++m) _Pragma("unroll") for (int n = 0; n < 2; ++n) _Pragma("unroll") for (int k = 0; k < 2; ++k) \
;         acc[ai][bj][m][n] = __builtin_amdgcn_mfma_f32_16x16x32_bf16(Bt[n][k], At[m][k], acc[ai][bj][m][n], 0, 0, 0); __builtin_amdgcn_s_setprio(0); } while (0)
; #define PG8_WAIT_V(n) asm volatile("s_waitcnt vmcnt(" #n ")" ::: "memory")
; #define PG8_WAIT_L(n) asm volatile("s_waitcnt lgkmcnt(" #n ")" ::: "memory")
; #define PG8_BAR __builtin_amdgcn_s_barrier()
; #define PG8_SCHED __builtin_amdgcn_sched_barrier(0)
; template <class Epi, class Sched, bool ALIGN_EPI = false, bool SP2 = false>
; __device__ __forceinline__ void gemm_phase(LAS unsigned char* lds, const Gemm g, const Sched& S, const Epi& E) {
;     ...
;             PG8_WAIT_V(8); PG8_WAIT_L(0); PG8_BAR; PG8_MMA(1, 0, At, B0); PG8_MMA(1, 1, At, B1); PG8_BAR; PG8_SCHED;
;             PG8_LDB(B0, 1, 0); PG8_LDB(B1, 1, 1); PG8_SCHED; PG8_LDA(At, 1, 0); PG8_STAGE(PG8_SA(0, 1), a2 + hstep, voffA);
;             PG8_WAIT_V(8); PG8_WAIT_L(0); PG8_BAR; PG8_MMA(0, 0, At, B0); PG8_MMA(0, 1, At, B1); PG8_BAR; PG8_SCHED;
;             PG8_LDA(At, 1, 1); PG8_STAGE(PG8_SB(1, 0), b3, voffB); PG8_STAGE(PG8_SB(1, 1), b3 + hstep, voffB); PG8_STAGE(PG8_SA(1, 0), a3, voffA);
	s_setprio 1
	s_waitcnt lgkmcnt(0)
	v_mfma_f32_16x16x32_bf16 v[62:65], v[90:93], v[162:165], v[62:65]
	v_mfma_f32_16x16x32_bf16 v[58:61], v[114:117], v[162:165], v[58:61]
	v_mfma_f32_16x16x32_bf16 v[42:45], v[114:117], v[170:173], v[42:45]
	v_mfma_f32_16x16x32_bf16 v[46:49], v[90:93], v[170:173], v[46:49]
	v_mfma_f32_16x16x32_bf16 v[30:33], v[90:93], v[178:181], v[30:33]
	v_mfma_f32_16x16x32_bf16 v[26:29], v[114:117], v[178:181], v[26:29]
	v_mfma_f32_16x16x32_bf16 v[10:13], v[114:117], v[204:207], v[10:13]
	v_mfma_f32_16x16x32_bf16 v[14:17], v[90:93], v[204:207], v[14:17]
	v_mfma_f32_16x16x32_bf16 v[62:65], v[102:105], v[166:169], v[62:65]
	v_mfma_f32_16x16x32_bf16 v[58:61], v[126:129], v[166:169], v[58:61]
	v_mfma_f32_16x16x32_bf16 v[42:45], v[126:129], v[174:177], v[42:45]
	v_mfma_f32_16x16x32_bf16 v[46:49], v[102:105], v[174:177], v[46:49]
	v_mfma_f32_16x16x32_bf16 v[30:33], v[102:105], v[182:185], v[30:33]
	v_mfma_f32_16x16x32_bf16 v[26:29], v[126:129], v[182:185], v[26:29]
	v_mfma_f32_16x16x32_bf16 v[10:13], v[126:129], v[208:211], v[10:13]
	v_mfma_f32_16x16x32_bf16 v[14:17], v[102:105], v[208:211], v[14:17]
	s_setprio 0
	s_setprio 1
	v_mfma_f32_16x16x32_bf16 v[54:57], v[138:141], v[162:165], v[54:57]
	v_mfma_f32_16x16x32_bf16 v[50:53], v[154:157], v[162:165], v[50:53]
	v_mfma_f32_16x16x32_bf16 v[34:37], v[154:157], v[170:173], v[34:37]
	v_mfma_f32_16x16x32_bf16 v[38:41], v[138:141], v[170:173], v[38:41]
	v_mfma_f32_16x16x32_bf16 v[22:25], v[138:141], v[178:181], v[22:25]
	v_mfma_f32_16x16x32_bf16 v[18:21], v[154:157], v[178:181], v[18:21]
	v_mfma_f32_16x16x32_bf16 v[2:5], v[154:157], v[204:207], v[2:5]
	v_mfma_f32_16x16x32_bf16 v[6:9], v[138:141], v[204:207], v[6:9]
	v_mfma_f32_16x16x32_bf16 v[54:57], v[142:145], v[166:169], v[54:57]
	v_mfma_f32_16x16x32_bf16 v[50:53], v[158:161], v[166:169], v[50:53]
	v_mfma_f32_16x16x32_bf16 v[34:37], v[158:161], v[174:177], v[34:37]
	v_mfma_f32_16x16x32_bf16 v[38:41], v[142:145], v[174:177], v[38:41]
	v_mfma_f32_16x16x32_bf16 v[22:25], v[142:145], v[182:185], v[22:25]
	v_mfma_f32_16x16x32_bf16 v[18:21], v[158:161], v[182:185], v[18:21]
	v_mfma_f32_16x16x32_bf16 v[2:5], v[158:161], v[208:211], v[2:5]
	v_mfma_f32_16x16x32_bf16 v[6:9], v[142:145], v[208:211], v[6:9]
	s_setprio 0
	s_barrier
	s_add_i32 s50, 0, 0x18000
	s_add_i32 s51, 0, 0x1c000
	v_add_u32_e32 v126, s50, v247
	v_add_u32_e32 v158, s51, v247
	ds_read_b128 v[90:93], v126
	ds_read_b128 v[102:105], v126 offset:1024
	ds_read_b128 v[114:117], v126 offset:2048
	ds_read_b128 v[126:129], v126 offset:3072
	ds_read_b128 v[138:141], v158
	ds_read_b128 v[142:145], v158 offset:1024
	ds_read_b128 v[154:157], v158 offset:2048
	ds_read_b128 v[158:161], v158 offset:3072
	s_add_u32 s22, s28, 0x160000
	s_addc_u32 s23, s29, 0
	s_mov_b32 m0, s8
	v_lshl_add_u64 v[212:213], s[22:23], 0, v[198:199]
	ds_read_b128 v[162:165], v249 offset:32768
	ds_read_b128 v[166:169], v249 offset:33792
	ds_read_b128 v[170:173], v249 offset:34816
	ds_read_b128 v[174:177], v249 offset:35840
	ds_read_b128 v[178:181], v249 offset:36864
	ds_read_b128 v[182:185], v249 offset:37888
	ds_read_b128 v[204:207], v249 offset:38912
	ds_read_b128 v[208:211], v249 offset:39936
	global_load_lds_dwordx4 v[212:213], off
	v_lshl_add_u64 v[212:213], s[22:23], 0, v[196:197]
	s_mov_b32 m0, s31
	s_nop 0
	global_load_lds_dwordx4 v[212:213], off
	s_waitcnt vmcnt(8)
	s_waitcnt lgkmcnt(0)
	s_barrier
	s_setprio 1
	s_waitcnt lgkmcnt(0)
	v_mfma_f32_16x16x32_bf16 v[150:153], v[90:93], v[162:165], v[150:153]
	v_mfma_f32_16x16x32_bf16 v[146:149], v[114:117], v[162:165], v[146:149]
	v_mfma_f32_16x16x32_bf16 v[118:121], v[114:117], v[170:173], v[118:121]
	v_mfma_f32_16x16x32_bf16 v[122:125], v[90:93], v[170:173], v[122:125]
	v_mfma_f32_16x16x32_bf16 v[98:101], v[90:93], v[178:181], v[98:101]
	v_mfma_f32_16x16x32_bf16 v[94:97], v[114:117], v[178:181], v[94:97]
	v_mfma_f32_16x16x32_bf16 v[74:77], v[114:117], v[204:207], v[74:77]
	v_mfma_f32_16x16x32_bf16 v[78:81], v[90:93], v[204:207], v[78:81]
	v_mfma_f32_16x16x32_bf16 v[150:153], v[102:105], v[166:169], v[150:153]
	v_mfma_f32_16x16x32_bf16 v[146:149], v[126:129], v[166:169], v[146:149]
	v_mfma_f32_16x16x32_bf16 v[118:121], v[126:129], v[174:177], v[118:121]
	v_mfma_f32_16x16x32_bf16 v[122:125], v[102:105], v[174:177], v[122:125]
	v_mfma_f32_16x16x32_bf16 v[98:101], v[102:105], v[182:185], v[98:101]
	v_mfma_f32_16x16x32_bf16 v[94:97], v[126:129], v[182:185], v[94:97]
	v_mfma_f32_16x16x32_bf16 v[74:77], v[126:129], v[208:211], v[74:77]
	v_mfma_f32_16x16x32_bf16 v[78:81], v[102:105], v[208:211], v[78:81]
	s_setprio 0
	s_setprio 1
	v_mfma_f32_16x16x32_bf16 v[134:137], v[138:141], v[162:165], v[134:137]
	v_mfma_f32_16x16x32_bf16 v[130:133], v[154:157], v[162:165], v[130:133]
	v_mfma_f32_16x16x32_bf16 v[106:109], v[154:157], v[170:173], v[106:109]
	v_mfma_f32_16x16x32_bf16 v[110:113], v[138:141], v[170:173], v[110:113]
	v_mfma_f32_16x16x32_bf16 v[86:89], v[138:141], v[178:181], v[86:89]
	v_mfma_f32_16x16x32_bf16 v[82:85], v[154:157], v[178:181], v[82:85]
	v_mfma_f32_16x16x32_bf16 v[66:69], v[154:157], v[204:207], v[66:69]
	v_mfma_f32_16x16x32_bf16 v[70:73], v[138:141], v[204:207], v[70:73]
	v_mfma_f32_16x16x32_bf16 v[134:137], v[142:145], v[166:169], v[134:137]
	v_mfma_f32_16x16x32_bf16 v[130:133], v[158:161], v[166:169], v[130:133]
	v_mfma_f32_16x16x32_bf16 v[106:109], v[158:161], v[174:177], v[106:109]
	v_mfma_f32_16x16x32_bf16 v[110:113], v[142:145], v[174:177], v[110:113]
	v_mfma_f32_16x16x32_bf16 v[86:89], v[142:145], v[182:185], v[86:89]
	v_mfma_f32_16x16x32_bf16 v[82:85], v[158:161], v[182:185], v[82:85]
	v_mfma_f32_16x16x32_bf16 v[66:69], v[158:161], v[208:211], v[66:69]
	v_mfma_f32_16x16x32_bf16 v[70:73], v[142:145], v[208:211], v[70:73]
	s_setprio 0
	s_barrier
; #define PG8_STAGE(bufoff, gbase, voff) do { _Pragma("unroll") for (int _i = 0; _i < 2; ++_i) \
;         __builtin_amdgcn_global_load_lds((const unsigned*)((const char*)(gbase) + (voff)[_i]), (LAS unsigned*)(lds + (bufoff) + ldsw + _i * 8192), 16, 0, 0); } while (0)
; #define PG8_LDA(dst, b, h) do { _Pragma("unroll") for (int m = 0; m < 4; ++m) _Pragma("unroll") for (int k = 0; k < 2; ++k) dst[m][k] = *(const LAS bf16x8*)(lds + PG8_SA(b, h) + aoff + m * 2048 + k * 1024); } while (0)
; #define PG8_MMA(ai, bj, At, Bt) do { __builtin_amdgcn_s_setprio(1); _Pragma("unroll") for (int m = 0; m < 4; ++m) _Pragma("unroll") for (int n = 0; n < 2; ++n) _Pragma("unroll") for (int k = 0; k < 2; ++k) \
;         acc[ai][bj][m][n] = __builtin_amdgcn_mfma_f32_16x16x32_bf16(Bt[n][k], At[m][k], acc[ai][bj][m][n], 0, 0, 0); __builtin_amdgcn_s_setprio(0); } while (0)
; #define PG8_WAIT_V(n) asm volatile("s_waitcnt vmcnt(" #n ")" ::: "memory")
; #define PG8_WAIT_L(n) asm volatile("s_waitcnt lgkmcnt(" #n ")" ::: "memory")
; #define PG8_BAR __builtin_amdgcn_s_barrier()
; #define PG8_SCHED __builtin_amdgcn_sched_barrier(0)
; template <class Epi, class Sched, bool ALIGN_EPI = false, bool SP2 = false>
; __device__ __forceinline__ void gemm_phase(LAS unsigned char* lds, const Gemm g, const Sched& S, const Epi& E) {
;     ...
;             PG8_LDA(At, 1, 1); PG8_STAGE(PG8_SB(1, 0), b3, voffB); PG8_STAGE(PG8_SB(1, 1), b3 + hstep, voffB); PG8_STAGE(PG8_SA(1, 0), a3, voffA);
;             PG8_WAIT_V(8); PG8_WAIT_L(0); PG8_BAR; PG8_MMA(1, 0, At, B0); PG8_MMA(1, 1, At, B1); PG8_BAR; PG8_SCHED;
;     ...
;         if constexpr (ALIGN_EPI) { if (wr == 0) PG8_BAR; }
	s_add_i32 s22, s50, s2
	v_lshl_add_u64 v[186:187], v[186:187], 0, s[12:13]
	s_mov_b32 m0, s22
	ds_read_b128 v[162:165], v249 offset:49152
	ds_read_b128 v[166:169], v249 offset:50176
	ds_read_b128 v[170:173], v249 offset:51200
	ds_read_b128 v[174:177], v249 offset:52224
	ds_read_b128 v[178:181], v249 offset:53248
	ds_read_b128 v[182:185], v249 offset:54272
	ds_read_b128 v[204:207], v249 offset:55296
	ds_read_b128 v[208:211], v249 offset:56320
	global_load_lds_dwordx4 v[186:187], off
	s_add_i32 m0, s22, 0x2000
	s_add_u32 s22, s26, 0x160080
	v_lshl_add_u64 v[186:187], v[188:189], 0, s[12:13]
	s_addc_u32 s23, s27, 0
	s_add_i32 s26, s51, s2
	global_load_lds_dwordx4 v[186:187], off
	v_lshl_add_u64 v[186:187], s[22:23], 0, v[0:1]
	s_mov_b32 m0, s26
	s_nop 0
	global_load_lds_dwordx4 v[186:187], off
	v_lshl_add_u64 v[186:187], s[22:23], 0, v[194:195]
	s_add_i32 m0, s26, 0x2000
	s_nop 0
	global_load_lds_dwordx4 v[186:187], off
	v_lshl_add_u64 v[186:187], v[190:191], 0, s[12:13]
	s_mov_b32 m0, s35
	s_nop 0
	global_load_lds_dwordx4 v[186:187], off
	v_lshl_add_u64 v[186:187], v[192:193], 0, s[12:13]
	s_mov_b32 m0, s40
	s_nop 0
	global_load_lds_dwordx4 v[186:187], off
	s_waitcnt vmcnt(8)
	s_waitcnt lgkmcnt(0)
	s_barrier
	s_setprio 1
	s_waitcnt lgkmcnt(0)
	v_mfma_f32_16x16x32_bf16 v[62:65], v[90:93], v[162:165], v[62:65]
	v_mfma_f32_16x16x32_bf16 v[58:61], v[114:117], v[162:165], v[58:61]
	v_mfma_f32_16x16x32_bf16 v[42:45], v[114:117], v[170:173], v[42:45]
	v_mfma_f32_16x16x32_bf16 v[46:49], v[90:93], v[170:173], v[46:49]
	v_mfma_f32_16x16x32_bf16 v[30:33], v[90:93], v[178:181], v[30:33]
	v_mfma_f32_16x16x32_bf16 v[26:29], v[114:117], v[178:181], v[26:29]
	v_mfma_f32_16x16x32_bf16 v[10:13], v[114:117], v[204:207], v[10:13]
	v_mfma_f32_16x16x32_bf16 v[14:17], v[90:93], v[204:207], v[14:17]
	v_mfma_f32_16x16x32_bf16 v[62:65], v[102:105], v[166:169], v[62:65]
	v_mfma_f32_16x16x32_bf16 v[58:61], v[126:129], v[166:169], v[58:61]
	v_mfma_f32_16x16x32_bf16 v[42:45], v[126:129], v[174:177], v[42:45]
	v_mfma_f32_16x16x32_bf16 v[46:49], v[102:105], v[174:177], v[46:49]
	v_mfma_f32_16x16x32_bf16 v[30:33], v[102:105], v[182:185], v[30:33]
	v_mfma_f32_16x16x32_bf16 v[26:29], v[126:129], v[182:185], v[26:29]
	v_mfma_f32_16x16x32_bf16 v[10:13], v[126:129], v[208:211], v[10:13]
	v_mfma_f32_16x16x32_bf16 v[14:17], v[102:105], v[208:211], v[14:17]
	s_setprio 0
	s_setprio 1
	v_mfma_f32_16x16x32_bf16 v[54:57], v[138:141], v[162:165], v[54:57]
	v_mfma_f32_16x16x32_bf16 v[50:53], v[154:157], v[162:165], v[50:53]
	v_mfma_f32_16x16x32_bf16 v[34:37], v[154:157], v[170:173], v[34:37]
	v_mfma_f32_16x16x32_bf16 v[38:41], v[138:141], v[170:173], v[38:41]
	v_mfma_f32_16x16x32_bf16 v[22:25], v[138:141], v[178:181], v[22:25]
	v_mfma_f32_16x16x32_bf16 v[18:21], v[154:157], v[178:181], v[18:21]
	v_mfma_f32_16x16x32_bf16 v[2:5], v[154:157], v[204:207], v[2:5]
	v_mfma_f32_16x16x32_bf16 v[6:9], v[138:141], v[204:207], v[6:9]
	v_mfma_f32_16x16x32_bf16 v[54:57], v[142:145], v[166:169], v[54:57]
	v_mfma_f32_16x16x32_bf16 v[50:53], v[158:161], v[166:169], v[50:53]
	v_mfma_f32_16x16x32_bf16 v[34:37], v[158:161], v[174:177], v[34:37]
	v_mfma_f32_16x16x32_bf16 v[38:41], v[142:145], v[174:177], v[38:41]
	v_mfma_f32_16x16x32_bf16 v[22:25], v[142:145], v[182:185], v[22:25]
	v_mfma_f32_16x16x32_bf16 v[18:21], v[158:161], v[182:185], v[18:21]
	v_mfma_f32_16x16x32_bf16 v[2:5], v[158:161], v[208:211], v[2:5]
	v_mfma_f32_16x16x32_bf16 v[6:9], v[142:145], v[208:211], v[6:9]
	s_setprio 0
	s_barrier
	s_add_i32 s49, s49, 2
	s_add_u32 s47, s47, 0x100
	s_addc_u32 s48, s48, 0
	s_cmpk_gt_u32 s49, 0x55
	s_mov_b64 s[22:23], s[24:25]
	s_cbranch_scc0 .LBB0_257
	s_and_b64 vcc, exec, s[18:19]
	s_cbranch_vccz .LBB0_260
	s_barrier

; #define PG8_STAGE(bufoff, gbase, voff) do { _Pragma("unroll") for (int _i = 0; _i < 2; ++_i) \
;         __builtin_amdgcn_global_load_lds((const unsigned*)((const char*)(gbase) + (voff)[_i]), (LAS unsigned*)(lds + (bufoff) + ldsw + _i * 8192), 16, 0, 0); } while (0)
; #define PG8_LDA(dst, b, h) do { _Pragma("unroll") for (int m = 0; m < 4; ++m) _Pragma("unroll") for (int k = 0; k < 2; ++k) dst[m][k] = *(const LAS bf16x8*)(lds + PG8_SA(b, h) + aoff + m * 2048 + k * 1024); } while (0)
; #define PG8_LDB(dst, b, h) do { _Pragma("unroll") for (int n = 0; n < 2; ++n) _Pragma("unroll") for (int k = 0; k < 2; ++k) dst[n][k] = *(const LAS bf16x8*)(lds + PG8_SB(b, h) + boff + n * 2048 + k * 1024); } while (0)
; #define PG8_MMA(ai, bj, At, Bt) do { __builtin_amdgcn_s_setprio(1); _Pragma("unroll") for (int m = 0; m < 4; ++m) _Pragma("unroll") for (int n = 0; n < 2; ++n) _Pragma("unroll") for (int k = 0; k < 2; ++k) \
;         acc[ai][bj][m][n] = __builtin_amdgcn_mfma_f32_16x16x32_bf16(Bt[n][k], At[m][k], acc[ai][bj][m][n], 0, 0, 0); __builtin_amdgcn_s_setprio(0); } while (0)
; #define PG8_WAIT_V(n) asm volatile("s_waitcnt vmcnt(" #n ")" ::: "memory")
; #define PG8_WAIT_L(n) asm volatile("s_waitcnt lgkmcnt(" #n ")" ::: "memory")
; template <class Epi, class Sched, bool ALIGN_EPI = false, bool SP2 = false>
; __device__ __forceinline__ void gemm_phase(LAS unsigned char* lds, const Gemm g, const Sched& S, const Epi& E) {
;     ...
;         for (int t = 0; t < nt; t += 2) {
;             const bool last = (t == nt - 2);
;             const char* a1 = cA + (size_t)(t + 1) * kstep;
;             const char* a2 = last ? nA : cA + (size_t)(t + 2) * kstep; const char* b2 = last ? nB : cB + (size_t)(t + 2) * kstep;
;             const char* a3 = a2 + kstep; const char* b3 = b2 + kstep;
;             if (last && has_next) S.a_ready(nxt);
;             if constexpr (SP2) {
;             PG8_LDB(B0, 0, 0); PG8_LDB(B1, 0, 1); PG8_SCHED; PG8_LDA(At, 0, 0); PG8_STAGE(PG8_SA(1, 1), a1 + hstep, voffA);
;             PG8_WAIT_V(8); PG8_WAIT_L(0); PG8_BAR; PG8_MMA(0, 0, At, B0); PG8_MMA(0, 1, At, B1); PG8_BAR; PG8_SCHED;
;             PG8_LDA(At, 0, 1); PG8_STAGE(PG8_SB(0, 0), b2, voffB); PG8_STAGE(PG8_SB(0, 1), b2 + hstep, voffB); PG8_STAGE(PG8_SA(0, 0), a2, voffA);
;             PG8_WAIT_V(8); PG8_WAIT_L(0); PG8_BAR; PG8_MMA(1, 0, At, B0); PG8_MMA(1, 1, At, B1); PG8_BAR; PG8_SCHED;
.LBB0_359:
	s_add_u32 s28, s26, 0xfff80080
	s_addc_u32 s29, s27, -1
	s_add_i32 s41, 0, 0x10000
	s_cmp_eq_u32 s40, 28
	s_cselect_b32 s31, s6, s29
	s_cselect_b32 s30, s7, s28
	v_add_u32_e32 v0, s41, v159
	s_cselect_b32 s29, s8, s35
	s_cselect_b32 s28, s19, s21
	s_add_i32 s57, 0, 0x14000
	ds_read_b128 v[142:145], v0
	ds_read_b128 v[146:149], v0 offset:1024
	ds_read_b128 v[150:153], v0 offset:2048
	ds_read_b128 v[154:157], v0 offset:3072
	v_add_u32_e32 v0, s57, v159
	ds_read_b128 v[162:165], v0
	ds_read_b128 v[166:169], v0 offset:1024
	ds_read_b128 v[170:173], v0 offset:2048
	ds_read_b128 v[174:177], v0 offset:3072
	v_lshl_add_u64 v[210:211], s[26:27], 0, v[138:139]
	s_add_i32 m0, s44, 0xc000
	ds_read_b128 v[178:181], v161
	ds_read_b128 v[182:185], v161 offset:1024
	ds_read_b128 v[186:189], v161 offset:2048
	ds_read_b128 v[190:193], v161 offset:3072
	ds_read_b128 v[194:197], v161 offset:4096
	ds_read_b128 v[198:201], v161 offset:5120
	ds_read_b128 v[202:205], v161 offset:6144
	ds_read_b128 v[206:209], v161 offset:7168
	global_load_lds_dwordx4 v[210:211], off
	v_lshl_add_u64 v[210:211], s[26:27], 0, v[140:141]
	s_add_i32 m0, s44, 0xe000
	s_nop 0
	global_load_lds_dwordx4 v[210:211], off
	s_waitcnt vmcnt(8)
	s_waitcnt lgkmcnt(0)
	s_barrier
	s_setprio 1
	s_waitcnt lgkmcnt(0)
	v_mfma_f32_16x16x32_bf16 v[126:129], v[142:145], v[178:181], v[126:129]
	v_mfma_f32_16x16x32_bf16 v[122:125], v[150:153], v[178:181], v[122:125]
	v_mfma_f32_16x16x32_bf16 v[106:109], v[150:153], v[186:189], v[106:109]
	v_mfma_f32_16x16x32_bf16 v[110:113], v[142:145], v[186:189], v[110:113]
	v_mfma_f32_16x16x32_bf16 v[94:97], v[142:145], v[194:197], v[94:97]
	v_mfma_f32_16x16x32_bf16 v[90:93], v[150:153], v[194:197], v[90:93]
	v_mfma_f32_16x16x32_bf16 v[74:77], v[150:153], v[202:205], v[74:77]
	v_mfma_f32_16x16x32_bf16 v[78:81], v[142:145], v[202:205], v[78:81]
	v_mfma_f32_16x16x32_bf16 v[126:129], v[146:149], v[182:185], v[126:129]
	v_mfma_f32_16x16x32_bf16 v[122:125], v[154:157], v[182:185], v[122:125]
	v_mfma_f32_16x16x32_bf16 v[106:109], v[154:157], v[190:193], v[106:109]
	v_mfma_f32_16x16x32_bf16 v[110:113], v[146:149], v[190:193], v[110:113]
	v_mfma_f32_16x16x32_bf16 v[94:97], v[146:149], v[198:201], v[94:97]
	v_mfma_f32_16x16x32_bf16 v[90:93], v[154:157], v[198:201], v[90:93]
	v_mfma_f32_16x16x32_bf16 v[74:77], v[154:157], v[206:209], v[74:77]
	v_mfma_f32_16x16x32_bf16 v[78:81], v[146:149], v[206:209], v[78:81]
	s_setprio 0
	s_setprio 1
	v_mfma_f32_16x16x32_bf16 v[118:121], v[162:165], v[178:181], v[118:121]
	v_mfma_f32_16x16x32_bf16 v[114:117], v[170:173], v[178:181], v[114:117]
	v_mfma_f32_16x16x32_bf16 v[98:101], v[170:173], v[186:189], v[98:101]
	v_mfma_f32_16x16x32_bf16 v[102:105], v[162:165], v[186:189], v[102:105]
	v_mfma_f32_16x16x32_bf16 v[86:89], v[162:165], v[194:197], v[86:89]
	v_mfma_f32_16x16x32_bf16 v[82:85], v[170:173], v[194:197], v[82:85]
	v_mfma_f32_16x16x32_bf16 v[66:69], v[170:173], v[202:205], v[66:69]
	v_mfma_f32_16x16x32_bf16 v[70:73], v[162:165], v[202:205], v[70:73]
	v_mfma_f32_16x16x32_bf16 v[118:121], v[166:169], v[182:185], v[118:121]
	v_mfma_f32_16x16x32_bf16 v[114:117], v[174:177], v[182:185], v[114:117]
	v_mfma_f32_16x16x32_bf16 v[98:101], v[174:177], v[190:193], v[98:101]
	v_mfma_f32_16x16x32_bf16 v[102:105], v[166:169], v[190:193], v[102:105]
	v_mfma_f32_16x16x32_bf16 v[86:89], v[166:169], v[198:201], v[86:89]
	v_mfma_f32_16x16x32_bf16 v[82:85], v[174:177], v[198:201], v[82:85]
	v_mfma_f32_16x16x32_bf16 v[66:69], v[174:177], v[206:209], v[66:69]
	v_mfma_f32_16x16x32_bf16 v[70:73], v[166:169], v[206:209], v[70:73]
	s_setprio 0
	s_barrier
	s_add_i32 s41, s41, s9
	v_lshl_add_u64 v[210:211], s[28:29], 0, v[134:135]
	s_mov_b32 m0, s41
	ds_read_b128 v[178:181], v161 offset:16384
	ds_read_b128 v[182:185], v161 offset:17408
	ds_read_b128 v[186:189], v161 offset:18432
	ds_read_b128 v[190:193], v161 offset:19456
	ds_read_b128 v[194:197], v161 offset:20480
	ds_read_b128 v[198:201], v161 offset:21504
	ds_read_b128 v[202:205], v161 offset:22528
	ds_read_b128 v[206:209], v161 offset:23552
	global_load_lds_dwordx4 v[210:211], off
	s_add_i32 m0, s41, 0x2000
	s_add_u32 s58, s28, 0x80000
	v_lshl_add_u64 v[212:213], s[28:29], 0, v[130:131]
	s_addc_u32 s59, s29, 0
	s_add_i32 s41, s57, s9
	global_load_lds_dwordx4 v[212:213], off
	v_lshl_add_u64 v[214:215], s[58:59], 0, v[134:135]
	s_mov_b32 m0, s41
	v_lshl_add_u64 v[216:217], s[30:31], 0, v[132:133]
	global_load_lds_dwordx4 v[214:215], off
	v_lshl_add_u64 v[214:215], s[58:59], 0, v[130:131]
	s_add_i32 m0, s41, 0x2000
	s_nop 0
	global_load_lds_dwordx4 v[214:215], off
	v_lshl_add_u64 v[214:215], s[30:31], 0, v[136:137]
	s_mov_b32 m0, s44
	s_nop 0
	global_load_lds_dwordx4 v[214:215], off
	s_mov_b32 m0, s45
	s_nop 0
	global_load_lds_dwordx4 v[216:217], off
	s_waitcnt vmcnt(8)
	s_waitcnt lgkmcnt(0)
	s_barrier
; #define PG8_STAGE(bufoff, gbase, voff) do { _Pragma("unroll") for (int _i = 0; _i < 2; ++_i) \
;         __builtin_amdgcn_global_load_lds((const unsigned*)((const char*)(gbase) + (voff)[_i]), (LAS unsigned*)(lds + (bufoff) + ldsw + _i * 8192), 16, 0, 0); } while (0)
; #define PG8_LDA(dst, b, h) do { _Pragma("unroll") for (int m = 0; m < 4; ++m) _Pragma("unroll") for (int k = 0; k < 2; ++k) dst[m][k] = *(const LAS bf16x8*)(lds + PG8_SA(b, h) + aoff + m * 2048 + k * 1024); } while (0)
; #define PG8_LDB(dst, b, h) do { _Pragma("unroll") for (int n = 0; n < 2; ++n) _Pragma("unroll") for (int k = 0; k < 2; ++k) dst[n][k] = *(const LAS bf16x8*)(lds + PG8_SB(b, h) + boff + n * 2048 + k * 1024); } while (0)
; #define PG8_MMA(ai, bj, At, Bt) do { __builtin_amdgcn_s_setprio(1); _Pragma("unroll") for (int m = 0; m < 4; ++m) _Pragma("unroll") for (int n = 0; n < 2; ++n) _Pragma("unroll") for (int k = 0; k < 2; ++k) \
;         acc[ai][bj][m][n] = __builtin_amdgcn_mfma_f32_16x16x32_bf16(Bt[n][k], At[m][k], acc[ai][bj][m][n], 0, 0, 0); __builtin_amdgcn_s_setprio(0); } while (0)
; #define PG8_WAIT_V(n) asm volatile("s_waitcnt vmcnt(" #n ")" ::: "memory")
; #define PG8_WAIT_L(n) asm volatile("s_waitcnt lgkmcnt(" #n ")" ::: "memory")
; #define PG8_BAR __builtin_amdgcn_s_barrier()
; #define PG8_SCHED __builtin_amdgcn_sched_barrier(0)
; template <class Epi, class Sched, bool ALIGN_EPI = false, bool SP2 = false>
; __device__ __forceinline__ void gemm_phase(LAS unsigned char* lds, const Gemm g, const Sched& S, const Epi& E) {
;     ...
;             PG8_WAIT_V(8); PG8_WAIT_L(0); PG8_BAR; PG8_MMA(1, 0, At, B0); PG8_MMA(1, 1, At, B1); PG8_BAR; PG8_SCHED;
;             PG8_LDB(B0, 1, 0); PG8_LDB(B1, 1, 1); PG8_SCHED; PG8_LDA(At, 1, 0); PG8_STAGE(PG8_SA(0, 1), a2 + hstep, voffA);
;             PG8_WAIT_V(8); PG8_WAIT_L(0); PG8_BAR; PG8_MMA(0, 0, At, B0); PG8_MMA(0, 1, At, B1); PG8_BAR; PG8_SCHED;
;             PG8_LDA(At, 1, 1); PG8_STAGE(PG8_SB(1, 0), b3, voffB); PG8_STAGE(PG8_SB(1, 1), b3 + hstep, voffB); PG8_STAGE(PG8_SA(1, 0), a3, voffA);
	s_setprio 1
	s_waitcnt lgkmcnt(0)
	v_mfma_f32_16x16x32_bf16 v[62:65], v[142:145], v[178:181], v[62:65]
	v_mfma_f32_16x16x32_bf16 v[58:61], v[150:153], v[178:181], v[58:61]
	v_mfma_f32_16x16x32_bf16 v[42:45], v[150:153], v[186:189], v[42:45]
	v_mfma_f32_16x16x32_bf16 v[46:49], v[142:145], v[186:189], v[46:49]
	v_mfma_f32_16x16x32_bf16 v[30:33], v[142:145], v[194:197], v[30:33]
	v_mfma_f32_16x16x32_bf16 v[26:29], v[150:153], v[194:197], v[26:29]
	v_mfma_f32_16x16x32_bf16 v[10:13], v[150:153], v[202:205], v[10:13]
	v_mfma_f32_16x16x32_bf16 v[14:17], v[142:145], v[202:205], v[14:17]
	v_mfma_f32_16x16x32_bf16 v[62:65], v[146:149], v[182:185], v[62:65]
	v_mfma_f32_16x16x32_bf16 v[58:61], v[154:157], v[182:185], v[58:61]
	v_mfma_f32_16x16x32_bf16 v[42:45], v[154:157], v[190:193], v[42:45]
	v_mfma_f32_16x16x32_bf16 v[46:49], v[146:149], v[190:193], v[46:49]
	v_mfma_f32_16x16x32_bf16 v[30:33], v[146:149], v[198:201], v[30:33]
	v_mfma_f32_16x16x32_bf16 v[26:29], v[154:157], v[198:201], v[26:29]
	v_mfma_f32_16x16x32_bf16 v[10:13], v[154:157], v[206:209], v[10:13]
	v_mfma_f32_16x16x32_bf16 v[14:17], v[146:149], v[206:209], v[14:17]
	s_setprio 0
	s_setprio 1
	v_mfma_f32_16x16x32_bf16 v[54:57], v[162:165], v[178:181], v[54:57]
	v_mfma_f32_16x16x32_bf16 v[50:53], v[170:173], v[178:181], v[50:53]
	v_mfma_f32_16x16x32_bf16 v[34:37], v[170:173], v[186:189], v[34:37]
	v_mfma_f32_16x16x32_bf16 v[38:41], v[162:165], v[186:189], v[38:41]
	v_mfma_f32_16x16x32_bf16 v[22:25], v[162:165], v[194:197], v[22:25]
	v_mfma_f32_16x16x32_bf16 v[18:21], v[170:173], v[194:197], v[18:21]
	v_mfma_f32_16x16x32_bf16 v[2:5], v[170:173], v[202:205], v[2:5]
	v_mfma_f32_16x16x32_bf16 v[6:9], v[162:165], v[202:205], v[6:9]
	v_mfma_f32_16x16x32_bf16 v[54:57], v[166:169], v[182:185], v[54:57]
	v_mfma_f32_16x16x32_bf16 v[50:53], v[174:177], v[182:185], v[50:53]
	v_mfma_f32_16x16x32_bf16 v[34:37], v[174:177], v[190:193], v[34:37]
	v_mfma_f32_16x16x32_bf16 v[38:41], v[166:169], v[190:193], v[38:41]
	v_mfma_f32_16x16x32_bf16 v[22:25], v[166:169], v[198:201], v[22:25]
	v_mfma_f32_16x16x32_bf16 v[18:21], v[174:177], v[198:201], v[18:21]
	v_mfma_f32_16x16x32_bf16 v[2:5], v[174:177], v[206:209], v[2:5]
	v_mfma_f32_16x16x32_bf16 v[6:9], v[166:169], v[206:209], v[6:9]
	s_setprio 0
	s_barrier
	s_add_i32 s41, 0, 0x18000
	v_add_u32_e32 v0, s41, v159
	s_add_i32 s57, 0, 0x1c000
	ds_read_b128 v[142:145], v0
	ds_read_b128 v[146:149], v0 offset:1024
	ds_read_b128 v[150:153], v0 offset:2048
	ds_read_b128 v[154:157], v0 offset:3072
	v_add_u32_e32 v0, s57, v159
	ds_read_b128 v[162:165], v0
	ds_read_b128 v[166:169], v0 offset:1024
	ds_read_b128 v[170:173], v0 offset:2048
	ds_read_b128 v[174:177], v0 offset:3072
	s_add_u32 s30, s30, 0x80000
	s_addc_u32 s31, s31, 0
	s_mov_b32 m0, s47
	v_lshl_add_u64 v[218:219], s[30:31], 0, v[136:137]
	ds_read_b128 v[178:181], v161 offset:32768
	ds_read_b128 v[182:185], v161 offset:33792
	ds_read_b128 v[186:189], v161 offset:34816
	ds_read_b128 v[190:193], v161 offset:35840
	ds_read_b128 v[194:197], v161 offset:36864
	ds_read_b128 v[198:201], v161 offset:37888
	ds_read_b128 v[202:205], v161 offset:38912
	ds_read_b128 v[206:209], v161 offset:39936
	global_load_lds_dwordx4 v[218:219], off
	v_lshl_add_u64 v[218:219], s[30:31], 0, v[132:133]
	s_mov_b32 m0, s48
	s_nop 0
	global_load_lds_dwordx4 v[218:219], off
	s_waitcnt vmcnt(8)
	s_waitcnt lgkmcnt(0)
	s_barrier
	s_setprio 1
	s_waitcnt lgkmcnt(0)
	v_mfma_f32_16x16x32_bf16 v[126:129], v[142:145], v[178:181], v[126:129]
	v_mfma_f32_16x16x32_bf16 v[122:125], v[150:153], v[178:181], v[122:125]
	v_mfma_f32_16x16x32_bf16 v[106:109], v[150:153], v[186:189], v[106:109]
	v_mfma_f32_16x16x32_bf16 v[110:113], v[142:145], v[186:189], v[110:113]
	v_mfma_f32_16x16x32_bf16 v[94:97], v[142:145], v[194:197], v[94:97]
	v_mfma_f32_16x16x32_bf16 v[90:93], v[150:153], v[194:197], v[90:93]
	v_mfma_f32_16x16x32_bf16 v[74:77], v[150:153], v[202:205], v[74:77]
	v_mfma_f32_16x16x32_bf16 v[78:81], v[142:145], v[202:205], v[78:81]
	v_mfma_f32_16x16x32_bf16 v[126:129], v[146:149], v[182:185], v[126:129]
	v_mfma_f32_16x16x32_bf16 v[122:125], v[154:157], v[182:185], v[122:125]
	v_mfma_f32_16x16x32_bf16 v[106:109], v[154:157], v[190:193], v[106:109]
	v_mfma_f32_16x16x32_bf16 v[110:113], v[146:149], v[190:193], v[110:113]
	v_mfma_f32_16x16x32_bf16 v[94:97], v[146:149], v[198:201], v[94:97]
	v_mfma_f32_16x16x32_bf16 v[90:93], v[154:157], v[198:201], v[90:93]
	v_mfma_f32_16x16x32_bf16 v[74:77], v[154:157], v[206:209], v[74:77]
	v_mfma_f32_16x16x32_bf16 v[78:81], v[146:149], v[206:209], v[78:81]
	s_setprio 0
	s_setprio 1
	v_mfma_f32_16x16x32_bf16 v[118:121], v[162:165], v[178:181], v[118:121]
	v_mfma_f32_16x16x32_bf16 v[114:117], v[170:173], v[178:181], v[114:117]
	v_mfma_f32_16x16x32_bf16 v[98:101], v[170:173], v[186:189], v[98:101]
	v_mfma_f32_16x16x32_bf16 v[102:105], v[162:165], v[186:189], v[102:105]
	v_mfma_f32_16x16x32_bf16 v[86:89], v[162:165], v[194:197], v[86:89]
	v_mfma_f32_16x16x32_bf16 v[82:85], v[170:173], v[194:197], v[82:85]
	v_mfma_f32_16x16x32_bf16 v[66:69], v[170:173], v[202:205], v[66:69]
	v_mfma_f32_16x16x32_bf16 v[70:73], v[162:165], v[202:205], v[70:73]
	v_mfma_f32_16x16x32_bf16 v[118:121], v[166:169], v[182:185], v[118:121]
	v_mfma_f32_16x16x32_bf16 v[114:117], v[174:177], v[182:185], v[114:117]
	v_mfma_f32_16x16x32_bf16 v[98:101], v[174:177], v[190:193], v[98:101]
	v_mfma_f32_16x16x32_bf16 v[102:105], v[166:169], v[190:193], v[102:105]
	v_mfma_f32_16x16x32_bf16 v[86:89], v[166:169], v[198:201], v[86:89]
	v_mfma_f32_16x16x32_bf16 v[82:85], v[174:177], v[198:201], v[82:85]
	v_mfma_f32_16x16x32_bf16 v[66:69], v[174:177], v[206:209], v[66:69]
	v_mfma_f32_16x16x32_bf16 v[70:73], v[166:169], v[206:209], v[70:73]
	s_setprio 0
	s_barrier
; #define PG8_STAGE(bufoff, gbase, voff) do { _Pragma("unroll") for (int _i = 0; _i < 2; ++_i) \
;         __builtin_amdgcn_global_load_lds((const unsigned*)((const char*)(gbase) + (voff)[_i]), (LAS unsigned*)(lds + (bufoff) + ldsw + _i * 8192), 16, 0, 0); } while (0)
; #define PG8_LDA(dst, b, h) do { _Pragma("unroll") for (int m = 0; m < 4; ++m) _Pragma("unroll") for (int k = 0; k < 2; ++k) dst[m][k] = *(const LAS bf16x8*)(lds + PG8_SA(b, h) + aoff + m * 2048 + k * 1024); } while (0)
; #define PG8_MMA(ai, bj, At, Bt) do { __builtin_amdgcn_s_setprio(1); _Pragma("unroll") for (int m = 0; m < 4; ++m) _Pragma("unroll") for (int n = 0; n < 2; ++n) _Pragma("unroll") for (int k = 0; k < 2; ++k) \
;         acc[ai][bj][m][n] = __builtin_amdgcn_mfma_f32_16x16x32_bf16(Bt[n][k], At[m][k], acc[ai][bj][m][n], 0, 0, 0); __builtin_amdgcn_s_setprio(0); } while (0)
; #define PG8_WAIT_V(n) asm volatile("s_waitcnt vmcnt(" #n ")" ::: "memory")
; #define PG8_WAIT_L(n) asm volatile("s_waitcnt lgkmcnt(" #n ")" ::: "memory")
; #define PG8_BAR __builtin_amdgcn_s_barrier()
; #define PG8_SCHED __builtin_amdgcn_sched_barrier(0)
; template <class Epi, class Sched, bool ALIGN_EPI = false, bool SP2 = false>
; __device__ __forceinline__ void gemm_phase(LAS unsigned char* lds, const Gemm g, const Sched& S, const Epi& E) {
;     ...
;             PG8_LDA(At, 1, 1); PG8_STAGE(PG8_SB(1, 0), b3, voffB); PG8_STAGE(PG8_SB(1, 1), b3 + hstep, voffB); PG8_STAGE(PG8_SA(1, 0), a3, voffA);
;             PG8_WAIT_V(8); PG8_WAIT_L(0); PG8_BAR; PG8_MMA(1, 0, At, B0); PG8_MMA(1, 1, At, B1); PG8_BAR; PG8_SCHED;
;     ...
;         if constexpr (ALIGN_EPI) { if (wr == 0) PG8_BAR; }
	s_add_i32 s30, s41, s9
	v_lshl_add_u64 v[210:211], v[210:211], 0, s[12:13]
	s_mov_b32 m0, s30
	ds_read_b128 v[178:181], v161 offset:49152
	ds_read_b128 v[182:185], v161 offset:50176
	ds_read_b128 v[186:189], v161 offset:51200
	ds_read_b128 v[190:193], v161 offset:52224
	ds_read_b128 v[194:197], v161 offset:53248
	ds_read_b128 v[198:201], v161 offset:54272
	ds_read_b128 v[202:205], v161 offset:55296
	ds_read_b128 v[206:209], v161 offset:56320
	global_load_lds_dwordx4 v[210:211], off
	s_add_i32 m0, s30, 0x2000
	s_add_u32 s28, s28, 0x80080
	v_lshl_add_u64 v[210:211], v[212:213], 0, s[12:13]
	s_addc_u32 s29, s29, 0
	s_add_i32 s30, s57, s9
	global_load_lds_dwordx4 v[210:211], off
	v_lshl_add_u64 v[210:211], s[28:29], 0, v[134:135]
	s_mov_b32 m0, s30
	s_nop 0
	global_load_lds_dwordx4 v[210:211], off
	v_lshl_add_u64 v[210:211], s[28:29], 0, v[130:131]
	s_add_i32 m0, s30, 0x2000
	s_nop 0
	global_load_lds_dwordx4 v[210:211], off
	v_lshl_add_u64 v[210:211], v[214:215], 0, s[12:13]
	s_mov_b32 m0, s53
	s_nop 0
	global_load_lds_dwordx4 v[210:211], off
	v_lshl_add_u64 v[210:211], v[216:217], 0, s[12:13]
	s_mov_b32 m0, s54
	s_nop 0
	global_load_lds_dwordx4 v[210:211], off
	s_waitcnt vmcnt(8)
	s_waitcnt lgkmcnt(0)
	s_barrier
	s_setprio 1
	s_waitcnt lgkmcnt(0)
	v_mfma_f32_16x16x32_bf16 v[62:65], v[142:145], v[178:181], v[62:65]
	v_mfma_f32_16x16x32_bf16 v[58:61], v[150:153], v[178:181], v[58:61]
	v_mfma_f32_16x16x32_bf16 v[42:45], v[150:153], v[186:189], v[42:45]
	v_mfma_f32_16x16x32_bf16 v[46:49], v[142:145], v[186:189], v[46:49]
	v_mfma_f32_16x16x32_bf16 v[30:33], v[142:145], v[194:197], v[30:33]
	v_mfma_f32_16x16x32_bf16 v[26:29], v[150:153], v[194:197], v[26:29]
	v_mfma_f32_16x16x32_bf16 v[10:13], v[150:153], v[202:205], v[10:13]
	v_mfma_f32_16x16x32_bf16 v[14:17], v[142:145], v[202:205], v[14:17]
	v_mfma_f32_16x16x32_bf16 v[62:65], v[146:149], v[182:185], v[62:65]
	v_mfma_f32_16x16x32_bf16 v[58:61], v[154:157], v[182:185], v[58:61]
	v_mfma_f32_16x16x32_bf16 v[42:45], v[154:157], v[190:193], v[42:45]
	v_mfma_f32_16x16x32_bf16 v[46:49], v[146:149], v[190:193], v[46:49]
	v_mfma_f32_16x16x32_bf16 v[30:33], v[146:149], v[198:201], v[30:33]
	v_mfma_f32_16x16x32_bf16 v[26:29], v[154:157], v[198:201], v[26:29]
	v_mfma_f32_16x16x32_bf16 v[10:13], v[154:157], v[206:209], v[10:13]
	v_mfma_f32_16x16x32_bf16 v[14:17], v[146:149], v[206:209], v[14:17]
	s_setprio 0
	s_setprio 1
	v_mfma_f32_16x16x32_bf16 v[54:57], v[162:165], v[178:181], v[54:57]
	v_mfma_f32_16x16x32_bf16 v[50:53], v[170:173], v[178:181], v[50:53]
	v_mfma_f32_16x16x32_bf16 v[34:37], v[170:173], v[186:189], v[34:37]
	v_mfma_f32_16x16x32_bf16 v[38:41], v[162:165], v[186:189], v[38:41]
	v_mfma_f32_16x16x32_bf16 v[22:25], v[162:165], v[194:197], v[22:25]
	v_mfma_f32_16x16x32_bf16 v[18:21], v[170:173], v[194:197], v[18:21]
	v_mfma_f32_16x16x32_bf16 v[2:5], v[170:173], v[202:205], v[2:5]
	v_mfma_f32_16x16x32_bf16 v[6:9], v[162:165], v[202:205], v[6:9]
	v_mfma_f32_16x16x32_bf16 v[54:57], v[166:169], v[182:185], v[54:57]
	v_mfma_f32_16x16x32_bf16 v[50:53], v[174:177], v[182:185], v[50:53]
	v_mfma_f32_16x16x32_bf16 v[34:37], v[174:177], v[190:193], v[34:37]
	v_mfma_f32_16x16x32_bf16 v[38:41], v[166:169], v[190:193], v[38:41]
	v_mfma_f32_16x16x32_bf16 v[22:25], v[166:169], v[198:201], v[22:25]
	v_mfma_f32_16x16x32_bf16 v[18:21], v[174:177], v[198:201], v[18:21]
	v_mfma_f32_16x16x32_bf16 v[2:5], v[174:177], v[206:209], v[2:5]
	v_mfma_f32_16x16x32_bf16 v[6:9], v[166:169], v[206:209], v[6:9]
	s_setprio 0
	s_barrier
	s_add_i32 s40, s40, 2
	s_add_u32 s26, s26, 0x100
	s_addc_u32 s27, s27, 0
	s_add_u32 s21, s21, 0x100
	s_addc_u32 s35, s35, 0
	s_cmp_gt_u32 s40, 29
	s_cbranch_scc0 .LBB0_359
	s_and_b64 vcc, exec, s[16:17]
	s_cbranch_vccz .LBB0_362
	s_barrier

; #define PG8_STAGE(bufoff, gbase, voff) do { _Pragma("unroll") for (int _i = 0; _i < 2; ++_i) \
;         __builtin_amdgcn_global_load_lds((const unsigned*)((const char*)(gbase) + (voff)[_i]), (LAS unsigned*)(lds + (bufoff) + ldsw + _i * 8192), 16, 0, 0); } while (0)
; #define PG8_LDA(dst, b, h) do { _Pragma("unroll") for (int m = 0; m < 4; ++m) _Pragma("unroll") for (int k = 0; k < 2; ++k) dst[m][k] = *(const LAS bf16x8*)(lds + PG8_SA(b, h) + aoff + m * 2048 + k * 1024); } while (0)
; #define PG8_LDB(dst, b, h) do { _Pragma("unroll") for (int n = 0; n < 2; ++n) _Pragma("unroll") for (int k = 0; k < 2; ++k) dst[n][k] = *(const LAS bf16x8*)(lds + PG8_SB(b, h) + boff + n * 2048 + k * 1024); } while (0)
; #define PG8_MMA(ai, bj, At, Bt) do { __builtin_amdgcn_s_setprio(1); _Pragma("unroll") for (int m = 0; m < 4; ++m) _Pragma("unroll") for (int n = 0; n < 2; ++n) _Pragma("unroll") for (int k = 0; k < 2; ++k) \
;         acc[ai][bj][m][n] = __builtin_amdgcn_mfma_f32_16x16x32_bf16(Bt[n][k], At[m][k], acc[ai][bj][m][n], 0, 0, 0); __builtin_amdgcn_s_setprio(0); } while (0)
; #define PG8_WAIT_V(n) asm volatile("s_waitcnt vmcnt(" #n ")" ::: "memory")
; #define PG8_WAIT_L(n) asm volatile("s_waitcnt lgkmcnt(" #n ")" ::: "memory")
; template <class Epi, class Sched, bool ALIGN_EPI = false, bool SP2 = false>
; __device__ __forceinline__ void gemm_phase(LAS unsigned char* lds, const Gemm g, const Sched& S, const Epi& E) {
;     ...
;         for (int t = 0; t < nt; t += 2) {
;             const bool last = (t == nt - 2);
;             const char* a1 = cA + (size_t)(t + 1) * kstep;
;             const char* a2 = last ? nA : cA + (size_t)(t + 2) * kstep; const char* b2 = last ? nB : cB + (size_t)(t + 2) * kstep;
;             const char* a3 = a2 + kstep; const char* b3 = b2 + kstep;
;             if (last && has_next) S.a_ready(nxt);
;             if constexpr (SP2) {
;             PG8_LDB(B0, 0, 0); PG8_LDB(B1, 0, 1); PG8_SCHED; PG8_LDA(At, 0, 0); PG8_STAGE(PG8_SA(1, 1), a1 + hstep, voffA);
;             PG8_WAIT_V(8); PG8_WAIT_L(0); PG8_BAR; PG8_MMA(0, 0, At, B0); PG8_MMA(0, 1, At, B1); PG8_BAR; PG8_SCHED;
;             PG8_LDA(At, 0, 1); PG8_STAGE(PG8_SB(0, 0), b2, voffB); PG8_STAGE(PG8_SB(0, 1), b2 + hstep, voffB); PG8_STAGE(PG8_SA(0, 0), a2, voffA);
;             PG8_WAIT_V(8); PG8_WAIT_L(0); PG8_BAR; PG8_MMA(1, 0, At, B0); PG8_MMA(1, 1, At, B1); PG8_BAR; PG8_SCHED;
.LBB0_833:
	s_add_u32 s28, s26, 0xfff80080
	s_addc_u32 s29, s27, -1
	s_add_i32 s53, 0, 0x10000
	s_cmp_eq_u32 s52, 28
	s_cselect_b32 s31, s21, s29
	s_cselect_b32 s30, s48, s28
	s_cselect_b32 s29, s19, s51
	s_cselect_b32 s28, s49, s50
	s_add_i32 s56, 0, 0x14000
	v_add_u32_e32 v134, s53, v247
	v_add_u32_e32 v158, s56, v247
	ds_read_b128 v[106:109], v134
	ds_read_b128 v[110:113], v134 offset:1024
	ds_read_b128 v[122:125], v134 offset:2048
	ds_read_b128 v[134:137], v134 offset:3072
	ds_read_b128 v[146:149], v158
	ds_read_b128 v[150:153], v158 offset:1024
	ds_read_b128 v[154:157], v158 offset:2048
	ds_read_b128 v[158:161], v158 offset:3072
	v_lshl_add_u64 v[204:205], s[26:27], 0, v[200:201]
	s_add_i32 m0, s8, 0xc000
	ds_read_b128 v[162:165], v249
	ds_read_b128 v[166:169], v249 offset:1024
	ds_read_b128 v[170:173], v249 offset:2048
	ds_read_b128 v[174:177], v249 offset:3072
	ds_read_b128 v[178:181], v249 offset:4096
	ds_read_b128 v[182:185], v249 offset:5120
	ds_read_b128 v[186:189], v249 offset:6144
	ds_read_b128 v[190:193], v249 offset:7168
	global_load_lds_dwordx4 v[204:205], off
	v_lshl_add_u64 v[204:205], s[26:27], 0, v[202:203]
	s_add_i32 m0, s8, 0xe000
	s_nop 0
	global_load_lds_dwordx4 v[204:205], off
	s_waitcnt vmcnt(8)
	s_waitcnt lgkmcnt(0)
	s_barrier
	s_setprio 1
	s_waitcnt lgkmcnt(0)
	v_mfma_f32_16x16x32_bf16 v[142:145], v[106:109], v[162:165], v[142:145]
	v_mfma_f32_16x16x32_bf16 v[138:141], v[122:125], v[162:165], v[138:141]
	v_mfma_f32_16x16x32_bf16 v[114:117], v[122:125], v[170:173], v[114:117]
	v_mfma_f32_16x16x32_bf16 v[118:121], v[106:109], v[170:173], v[118:121]
	v_mfma_f32_16x16x32_bf16 v[94:97], v[106:109], v[178:181], v[94:97]
	v_mfma_f32_16x16x32_bf16 v[90:93], v[122:125], v[178:181], v[90:93]
	v_mfma_f32_16x16x32_bf16 v[74:77], v[122:125], v[186:189], v[74:77]
	v_mfma_f32_16x16x32_bf16 v[78:81], v[106:109], v[186:189], v[78:81]
	v_mfma_f32_16x16x32_bf16 v[142:145], v[110:113], v[166:169], v[142:145]
	v_mfma_f32_16x16x32_bf16 v[138:141], v[134:137], v[166:169], v[138:141]
	v_mfma_f32_16x16x32_bf16 v[114:117], v[134:137], v[174:177], v[114:117]
	v_mfma_f32_16x16x32_bf16 v[118:121], v[110:113], v[174:177], v[118:121]
	v_mfma_f32_16x16x32_bf16 v[94:97], v[110:113], v[182:185], v[94:97]
	v_mfma_f32_16x16x32_bf16 v[90:93], v[134:137], v[182:185], v[90:93]
	v_mfma_f32_16x16x32_bf16 v[74:77], v[134:137], v[190:193], v[74:77]
	v_mfma_f32_16x16x32_bf16 v[78:81], v[110:113], v[190:193], v[78:81]
	s_setprio 0
	s_setprio 1
	v_mfma_f32_16x16x32_bf16 v[130:133], v[146:149], v[162:165], v[130:133]
	v_mfma_f32_16x16x32_bf16 v[126:129], v[154:157], v[162:165], v[126:129]
	v_mfma_f32_16x16x32_bf16 v[98:101], v[154:157], v[170:173], v[98:101]
	v_mfma_f32_16x16x32_bf16 v[102:105], v[146:149], v[170:173], v[102:105]
	v_mfma_f32_16x16x32_bf16 v[86:89], v[146:149], v[178:181], v[86:89]
	v_mfma_f32_16x16x32_bf16 v[82:85], v[154:157], v[178:181], v[82:85]
	v_mfma_f32_16x16x32_bf16 v[66:69], v[154:157], v[186:189], v[66:69]
	v_mfma_f32_16x16x32_bf16 v[70:73], v[146:149], v[186:189], v[70:73]
	v_mfma_f32_16x16x32_bf16 v[130:133], v[150:153], v[166:169], v[130:133]
	v_mfma_f32_16x16x32_bf16 v[126:129], v[158:161], v[166:169], v[126:129]
	v_mfma_f32_16x16x32_bf16 v[98:101], v[158:161], v[174:177], v[98:101]
	v_mfma_f32_16x16x32_bf16 v[102:105], v[150:153], v[174:177], v[102:105]
	v_mfma_f32_16x16x32_bf16 v[86:89], v[150:153], v[182:185], v[86:89]
	v_mfma_f32_16x16x32_bf16 v[82:85], v[158:161], v[182:185], v[82:85]
	v_mfma_f32_16x16x32_bf16 v[66:69], v[158:161], v[190:193], v[66:69]
	v_mfma_f32_16x16x32_bf16 v[70:73], v[150:153], v[190:193], v[70:73]
	s_setprio 0
	s_barrier
	s_add_i32 s53, s53, s7
	v_lshl_add_u64 v[204:205], s[28:29], 0, v[0:1]
	s_mov_b32 m0, s53
	ds_read_b128 v[162:165], v249 offset:16384
	ds_read_b128 v[166:169], v249 offset:17408
	ds_read_b128 v[170:173], v249 offset:18432
	ds_read_b128 v[174:177], v249 offset:19456
	ds_read_b128 v[178:181], v249 offset:20480
	ds_read_b128 v[182:185], v249 offset:21504
	ds_read_b128 v[186:189], v249 offset:22528
	ds_read_b128 v[190:193], v249 offset:23552
	global_load_lds_dwordx4 v[204:205], off
	s_add_i32 m0, s53, 0x2000
	s_add_u32 s54, s28, 0x80000
	v_lshl_add_u64 v[206:207], s[28:29], 0, v[194:195]
	s_addc_u32 s55, s29, 0
	s_add_i32 s53, s56, s7
	global_load_lds_dwordx4 v[206:207], off
	v_lshl_add_u64 v[208:209], s[54:55], 0, v[0:1]
	s_mov_b32 m0, s53
	v_lshl_add_u64 v[210:211], s[30:31], 0, v[196:197]
	global_load_lds_dwordx4 v[208:209], off
	v_lshl_add_u64 v[208:209], s[54:55], 0, v[194:195]
	s_add_i32 m0, s53, 0x2000
	s_nop 0
	global_load_lds_dwordx4 v[208:209], off
	v_lshl_add_u64 v[208:209], s[30:31], 0, v[198:199]
	s_mov_b32 m0, s8
	s_nop 0
	global_load_lds_dwordx4 v[208:209], off
	s_mov_b32 m0, s9
	s_nop 0
	global_load_lds_dwordx4 v[210:211], off
	s_waitcnt vmcnt(8)
	s_waitcnt lgkmcnt(0)
	s_barrier
; #define PG8_STAGE(bufoff, gbase, voff) do { _Pragma("unroll") for (int _i = 0; _i < 2; ++_i) \
;         __builtin_amdgcn_global_load_lds((const unsigned*)((const char*)(gbase) + (voff)[_i]), (LAS unsigned*)(lds + (bufoff) + ldsw + _i * 8192), 16, 0, 0); } while (0)
; #define PG8_LDA(dst, b, h) do { _Pragma("unroll") for (int m = 0; m < 4; ++m) _Pragma("unroll") for (int k = 0; k < 2; ++k) dst[m][k] = *(const LAS bf16x8*)(lds + PG8_SA(b, h) + aoff + m * 2048 + k * 1024); } while (0)
; #define PG8_LDB(dst, b, h) do { _Pragma("unroll") for (int n = 0; n < 2; ++n) _Pragma("unroll") for (int k = 0; k < 2; ++k) dst[n][k] = *(const LAS bf16x8*)(lds + PG8_SB(b, h) + boff + n * 2048 + k * 1024); } while (0)
; #define PG8_MMA(ai, bj, At, Bt) do { __builtin_amdgcn_s_setprio(1); _Pragma("unroll") for (int m = 0; m < 4; ++m) _Pragma("unroll") for (int n = 0; n < 2; ++n) _Pragma("unroll") for (int k = 0; k < 2; ++k) \
;         acc[ai][bj][m][n] = __builtin_amdgcn_mfma_f32_16x16x32_bf16(Bt[n][k], At[m][k], acc[ai][bj][m][n], 0, 0, 0); __builtin_amdgcn_s_setprio(0); } while (0)
; #define PG8_WAIT_V(n) asm volatile("s_waitcnt vmcnt(" #n ")" ::: "memory")
; #define PG8_WAIT_L(n) asm volatile("s_waitcnt lgkmcnt(" #n ")" ::: "memory")
; #define PG8_BAR __builtin_amdgcn_s_barrier()
; #define PG8_SCHED __builtin_amdgcn_sched_barrier(0)
; template <class Epi, class Sched, bool ALIGN_EPI = false, bool SP2 = false>
; __device__ __forceinline__ void gemm_phase(LAS unsigned char* lds, const Gemm g, const Sched& S, const Epi& E) {
;     ...
;             PG8_WAIT_V(8); PG8_WAIT_L(0); PG8_BAR; PG8_MMA(1, 0, At, B0); PG8_MMA(1, 1, At, B1); PG8_BAR; PG8_SCHED;
;             PG8_LDB(B0, 1, 0); PG8_LDB(B1, 1, 1); PG8_SCHED; PG8_LDA(At, 1, 0); PG8_STAGE(PG8_SA(0, 1), a2 + hstep, voffA);
;             PG8_WAIT_V(8); PG8_WAIT_L(0); PG8_BAR; PG8_MMA(0, 0, At, B0); PG8_MMA(0, 1, At, B1); PG8_BAR; PG8_SCHED;
;             PG8_LDA(At, 1, 1); PG8_STAGE(PG8_SB(1, 0), b3, voffB); PG8_STAGE(PG8_SB(1, 1), b3 + hstep, voffB); PG8_STAGE(PG8_SA(1, 0), a3, voffA);
	s_setprio 1
	s_waitcnt lgkmcnt(0)
	v_mfma_f32_16x16x32_bf16 v[62:65], v[106:109], v[162:165], v[62:65]
	v_mfma_f32_16x16x32_bf16 v[58:61], v[122:125], v[162:165], v[58:61]
	v_mfma_f32_16x16x32_bf16 v[42:45], v[122:125], v[170:173], v[42:45]
	v_mfma_f32_16x16x32_bf16 v[46:49], v[106:109], v[170:173], v[46:49]
	v_mfma_f32_16x16x32_bf16 v[30:33], v[106:109], v[178:181], v[30:33]
	v_mfma_f32_16x16x32_bf16 v[26:29], v[122:125], v[178:181], v[26:29]
	v_mfma_f32_16x16x32_bf16 v[10:13], v[122:125], v[186:189], v[10:13]
	v_mfma_f32_16x16x32_bf16 v[14:17], v[106:109], v[186:189], v[14:17]
	v_mfma_f32_16x16x32_bf16 v[62:65], v[110:113], v[166:169], v[62:65]
	v_mfma_f32_16x16x32_bf16 v[58:61], v[134:137], v[166:169], v[58:61]
	v_mfma_f32_16x16x32_bf16 v[42:45], v[134:137], v[174:177], v[42:45]
	v_mfma_f32_16x16x32_bf16 v[46:49], v[110:113], v[174:177], v[46:49]
	v_mfma_f32_16x16x32_bf16 v[30:33], v[110:113], v[182:185], v[30:33]
	v_mfma_f32_16x16x32_bf16 v[26:29], v[134:137], v[182:185], v[26:29]
	v_mfma_f32_16x16x32_bf16 v[10:13], v[134:137], v[190:193], v[10:13]
	v_mfma_f32_16x16x32_bf16 v[14:17], v[110:113], v[190:193], v[14:17]
	s_setprio 0
	s_setprio 1
	v_mfma_f32_16x16x32_bf16 v[54:57], v[146:149], v[162:165], v[54:57]
	v_mfma_f32_16x16x32_bf16 v[50:53], v[154:157], v[162:165], v[50:53]
	v_mfma_f32_16x16x32_bf16 v[34:37], v[154:157], v[170:173], v[34:37]
	v_mfma_f32_16x16x32_bf16 v[38:41], v[146:149], v[170:173], v[38:41]
	v_mfma_f32_16x16x32_bf16 v[22:25], v[146:149], v[178:181], v[22:25]
	v_mfma_f32_16x16x32_bf16 v[18:21], v[154:157], v[178:181], v[18:21]
	v_mfma_f32_16x16x32_bf16 v[2:5], v[154:157], v[186:189], v[2:5]
	v_mfma_f32_16x16x32_bf16 v[6:9], v[146:149], v[186:189], v[6:9]
	v_mfma_f32_16x16x32_bf16 v[54:57], v[150:153], v[166:169], v[54:57]
	v_mfma_f32_16x16x32_bf16 v[50:53], v[158:161], v[166:169], v[50:53]
	v_mfma_f32_16x16x32_bf16 v[34:37], v[158:161], v[174:177], v[34:37]
	v_mfma_f32_16x16x32_bf16 v[38:41], v[150:153], v[174:177], v[38:41]
	v_mfma_f32_16x16x32_bf16 v[22:25], v[150:153], v[182:185], v[22:25]
	v_mfma_f32_16x16x32_bf16 v[18:21], v[158:161], v[182:185], v[18:21]
	v_mfma_f32_16x16x32_bf16 v[2:5], v[158:161], v[190:193], v[2:5]
	v_mfma_f32_16x16x32_bf16 v[6:9], v[150:153], v[190:193], v[6:9]
	s_setprio 0
	s_barrier
	s_add_i32 s53, 0, 0x18000
	s_add_i32 s54, 0, 0x1c000
	v_add_u32_e32 v134, s53, v247
	v_add_u32_e32 v158, s54, v247
	ds_read_b128 v[106:109], v134
	ds_read_b128 v[110:113], v134 offset:1024
	ds_read_b128 v[122:125], v134 offset:2048
	ds_read_b128 v[134:137], v134 offset:3072
	ds_read_b128 v[146:149], v158
	ds_read_b128 v[150:153], v158 offset:1024
	ds_read_b128 v[154:157], v158 offset:2048
	ds_read_b128 v[158:161], v158 offset:3072
	s_add_u32 s30, s30, 0x80000
	s_addc_u32 s31, s31, 0
	s_mov_b32 m0, s35
	v_lshl_add_u64 v[212:213], s[30:31], 0, v[198:199]
	ds_read_b128 v[162:165], v249 offset:32768
	ds_read_b128 v[166:169], v249 offset:33792
	ds_read_b128 v[170:173], v249 offset:34816
	ds_read_b128 v[174:177], v249 offset:35840
	ds_read_b128 v[178:181], v249 offset:36864
	ds_read_b128 v[182:185], v249 offset:37888
	ds_read_b128 v[186:189], v249 offset:38912
	ds_read_b128 v[190:193], v249 offset:39936
	global_load_lds_dwordx4 v[212:213], off
	v_lshl_add_u64 v[212:213], s[30:31], 0, v[196:197]
	s_mov_b32 m0, s42
	s_nop 0
	global_load_lds_dwordx4 v[212:213], off
	s_waitcnt vmcnt(8)
	s_waitcnt lgkmcnt(0)
	s_barrier
	s_setprio 1
	s_waitcnt lgkmcnt(0)
	v_mfma_f32_16x16x32_bf16 v[142:145], v[106:109], v[162:165], v[142:145]
	v_mfma_f32_16x16x32_bf16 v[138:141], v[122:125], v[162:165], v[138:141]
	v_mfma_f32_16x16x32_bf16 v[114:117], v[122:125], v[170:173], v[114:117]
	v_mfma_f32_16x16x32_bf16 v[118:121], v[106:109], v[170:173], v[118:121]
	v_mfma_f32_16x16x32_bf16 v[94:97], v[106:109], v[178:181], v[94:97]
	v_mfma_f32_16x16x32_bf16 v[90:93], v[122:125], v[178:181], v[90:93]
	v_mfma_f32_16x16x32_bf16 v[74:77], v[122:125], v[186:189], v[74:77]
	v_mfma_f32_16x16x32_bf16 v[78:81], v[106:109], v[186:189], v[78:81]
	v_mfma_f32_16x16x32_bf16 v[142:145], v[110:113], v[166:169], v[142:145]
	v_mfma_f32_16x16x32_bf16 v[138:141], v[134:137], v[166:169], v[138:141]
	v_mfma_f32_16x16x32_bf16 v[114:117], v[134:137], v[174:177], v[114:117]
	v_mfma_f32_16x16x32_bf16 v[118:121], v[110:113], v[174:177], v[118:121]
	v_mfma_f32_16x16x32_bf16 v[94:97], v[110:113], v[182:185], v[94:97]
	v_mfma_f32_16x16x32_bf16 v[90:93], v[134:137], v[182:185], v[90:93]
	v_mfma_f32_16x16x32_bf16 v[74:77], v[134:137], v[190:193], v[74:77]
	v_mfma_f32_16x16x32_bf16 v[78:81], v[110:113], v[190:193], v[78:81]
	s_setprio 0
	s_setprio 1
	v_mfma_f32_16x16x32_bf16 v[130:133], v[146:149], v[162:165], v[130:133]
	v_mfma_f32_16x16x32_bf16 v[126:129], v[154:157], v[162:165], v[126:129]
	v_mfma_f32_16x16x32_bf16 v[98:101], v[154:157], v[170:173], v[98:101]
	v_mfma_f32_16x16x32_bf16 v[102:105], v[146:149], v[170:173], v[102:105]
	v_mfma_f32_16x16x32_bf16 v[86:89], v[146:149], v[178:181], v[86:89]
	v_mfma_f32_16x16x32_bf16 v[82:85], v[154:157], v[178:181], v[82:85]
	v_mfma_f32_16x16x32_bf16 v[66:69], v[154:157], v[186:189], v[66:69]
	v_mfma_f32_16x16x32_bf16 v[70:73], v[146:149], v[186:189], v[70:73]
	v_mfma_f32_16x16x32_bf16 v[130:133], v[150:153], v[166:169], v[130:133]
	v_mfma_f32_16x16x32_bf16 v[126:129], v[158:161], v[166:169], v[126:129]
	v_mfma_f32_16x16x32_bf16 v[98:101], v[158:161], v[174:177], v[98:101]
	v_mfma_f32_16x16x32_bf16 v[102:105], v[150:153], v[174:177], v[102:105]
	v_mfma_f32_16x16x32_bf16 v[86:89], v[150:153], v[182:185], v[86:89]
	v_mfma_f32_16x16x32_bf16 v[82:85], v[158:161], v[182:185], v[82:85]
	v_mfma_f32_16x16x32_bf16 v[66:69], v[158:161], v[190:193], v[66:69]
	v_mfma_f32_16x16x32_bf16 v[70:73], v[150:153], v[190:193], v[70:73]
	s_setprio 0
	s_barrier
; #define PG8_STAGE(bufoff, gbase, voff) do { _Pragma("unroll") for (int _i = 0; _i < 2; ++_i) \
;         __builtin_amdgcn_global_load_lds((const unsigned*)((const char*)(gbase) + (voff)[_i]), (LAS unsigned*)(lds + (bufoff) + ldsw + _i * 8192), 16, 0, 0); } while (0)
; #define PG8_LDA(dst, b, h) do { _Pragma("unroll") for (int m = 0; m < 4; ++m) _Pragma("unroll") for (int k = 0; k < 2; ++k) dst[m][k] = *(const LAS bf16x8*)(lds + PG8_SA(b, h) + aoff + m * 2048 + k * 1024); } while (0)
; #define PG8_MMA(ai, bj, At, Bt) do { __builtin_amdgcn_s_setprio(1); _Pragma("unroll") for (int m = 0; m < 4; ++m) _Pragma("unroll") for (int n = 0; n < 2; ++n) _Pragma("unroll") for (int k = 0; k < 2; ++k) \
;         acc[ai][bj][m][n] = __builtin_amdgcn_mfma_f32_16x16x32_bf16(Bt[n][k], At[m][k], acc[ai][bj][m][n], 0, 0, 0); __builtin_amdgcn_s_setprio(0); } while (0)
; #define PG8_WAIT_V(n) asm volatile("s_waitcnt vmcnt(" #n ")" ::: "memory")
; #define PG8_WAIT_L(n) asm volatile("s_waitcnt lgkmcnt(" #n ")" ::: "memory")
; #define PG8_BAR __builtin_amdgcn_s_barrier()
; #define PG8_SCHED __builtin_amdgcn_sched_barrier(0)
; template <class Epi, class Sched, bool ALIGN_EPI = false, bool SP2 = false>
; __device__ __forceinline__ void gemm_phase(LAS unsigned char* lds, const Gemm g, const Sched& S, const Epi& E) {
;     ...
;             PG8_LDA(At, 1, 1); PG8_STAGE(PG8_SB(1, 0), b3, voffB); PG8_STAGE(PG8_SB(1, 1), b3 + hstep, voffB); PG8_STAGE(PG8_SA(1, 0), a3, voffA);
;             PG8_WAIT_V(8); PG8_WAIT_L(0); PG8_BAR; PG8_MMA(1, 0, At, B0); PG8_MMA(1, 1, At, B1); PG8_BAR; PG8_SCHED;
;     ...
;         if constexpr (ALIGN_EPI) { if (wr == 0) PG8_BAR; }
	s_add_i32 s30, s53, s7
	v_lshl_add_u64 v[204:205], v[204:205], 0, s[12:13]
	s_mov_b32 m0, s30
	ds_read_b128 v[162:165], v249 offset:49152
	ds_read_b128 v[166:169], v249 offset:50176
	ds_read_b128 v[170:173], v249 offset:51200
	ds_read_b128 v[174:177], v249 offset:52224
	ds_read_b128 v[178:181], v249 offset:53248
	ds_read_b128 v[182:185], v249 offset:54272
	ds_read_b128 v[186:189], v249 offset:55296
	ds_read_b128 v[190:193], v249 offset:56320
	global_load_lds_dwordx4 v[204:205], off
	s_add_i32 m0, s30, 0x2000
	s_add_u32 s28, s28, 0x80080
	v_lshl_add_u64 v[204:205], v[206:207], 0, s[12:13]
	s_addc_u32 s29, s29, 0
	s_add_i32 s30, s54, s7
	global_load_lds_dwordx4 v[204:205], off
	v_lshl_add_u64 v[204:205], s[28:29], 0, v[0:1]
	s_mov_b32 m0, s30
	s_nop 0
	global_load_lds_dwordx4 v[204:205], off
	v_lshl_add_u64 v[204:205], s[28:29], 0, v[194:195]
	s_add_i32 m0, s30, 0x2000
	s_nop 0
	global_load_lds_dwordx4 v[204:205], off
	v_lshl_add_u64 v[204:205], v[208:209], 0, s[12:13]
	s_mov_b32 m0, s43
	s_nop 0
	global_load_lds_dwordx4 v[204:205], off
	v_lshl_add_u64 v[204:205], v[210:211], 0, s[12:13]
	s_mov_b32 m0, s44
	s_nop 0
	global_load_lds_dwordx4 v[204:205], off
	s_waitcnt vmcnt(8)
	s_waitcnt lgkmcnt(0)
	s_barrier
	s_setprio 1
	s_waitcnt lgkmcnt(0)
	v_mfma_f32_16x16x32_bf16 v[62:65], v[106:109], v[162:165], v[62:65]
	v_mfma_f32_16x16x32_bf16 v[58:61], v[122:125], v[162:165], v[58:61]
	v_mfma_f32_16x16x32_bf16 v[42:45], v[122:125], v[170:173], v[42:45]
	v_mfma_f32_16x16x32_bf16 v[46:49], v[106:109], v[170:173], v[46:49]
	v_mfma_f32_16x16x32_bf16 v[30:33], v[106:109], v[178:181], v[30:33]
	v_mfma_f32_16x16x32_bf16 v[26:29], v[122:125], v[178:181], v[26:29]
	v_mfma_f32_16x16x32_bf16 v[10:13], v[122:125], v[186:189], v[10:13]
	v_mfma_f32_16x16x32_bf16 v[14:17], v[106:109], v[186:189], v[14:17]
	v_mfma_f32_16x16x32_bf16 v[62:65], v[110:113], v[166:169], v[62:65]
	v_mfma_f32_16x16x32_bf16 v[58:61], v[134:137], v[166:169], v[58:61]
	v_mfma_f32_16x16x32_bf16 v[42:45], v[134:137], v[174:177], v[42:45]
	v_mfma_f32_16x16x32_bf16 v[46:49], v[110:113], v[174:177], v[46:49]
	v_mfma_f32_16x16x32_bf16 v[30:33], v[110:113], v[182:185], v[30:33]
	v_mfma_f32_16x16x32_bf16 v[26:29], v[134:137], v[182:185], v[26:29]
	v_mfma_f32_16x16x32_bf16 v[10:13], v[134:137], v[190:193], v[10:13]
	v_mfma_f32_16x16x32_bf16 v[14:17], v[110:113], v[190:193], v[14:17]
	s_setprio 0
	s_setprio 1
	v_mfma_f32_16x16x32_bf16 v[54:57], v[146:149], v[162:165], v[54:57]
	v_mfma_f32_16x16x32_bf16 v[50:53], v[154:157], v[162:165], v[50:53]
	v_mfma_f32_16x16x32_bf16 v[34:37], v[154:157], v[170:173], v[34:37]
	v_mfma_f32_16x16x32_bf16 v[38:41], v[146:149], v[170:173], v[38:41]
	v_mfma_f32_16x16x32_bf16 v[22:25], v[146:149], v[178:181], v[22:25]
	v_mfma_f32_16x16x32_bf16 v[18:21], v[154:157], v[178:181], v[18:21]
	v_mfma_f32_16x16x32_bf16 v[2:5], v[154:157], v[186:189], v[2:5]
	v_mfma_f32_16x16x32_bf16 v[6:9], v[146:149], v[186:189], v[6:9]
	v_mfma_f32_16x16x32_bf16 v[54:57], v[150:153], v[166:169], v[54:57]
	v_mfma_f32_16x16x32_bf16 v[50:53], v[158:161], v[166:169], v[50:53]
	v_mfma_f32_16x16x32_bf16 v[34:37], v[158:161], v[174:177], v[34:37]
	v_mfma_f32_16x16x32_bf16 v[38:41], v[150:153], v[174:177], v[38:41]
	v_mfma_f32_16x16x32_bf16 v[22:25], v[150:153], v[182:185], v[22:25]
	v_mfma_f32_16x16x32_bf16 v[18:21], v[158:161], v[182:185], v[18:21]
	v_mfma_f32_16x16x32_bf16 v[2:5], v[158:161], v[190:193], v[2:5]
	v_mfma_f32_16x16x32_bf16 v[6:9], v[150:153], v[190:193], v[6:9]
	s_setprio 0
	s_barrier
	s_add_i32 s52, s52, 2
	s_add_u32 s26, s26, 0x100
	s_addc_u32 s27, s27, 0
	s_add_u32 s50, s50, 0x100
	s_addc_u32 s51, s51, 0
	s_cmp_gt_u32 s52, 29
	s_cbranch_scc0 .LBB0_833
	s_and_b64 vcc, exec, s[16:17]
	s_cbranch_vccz .LBB0_836
	s_barrier

; #define PG8_STAGE(bufoff, gbase, voff) do { _Pragma("unroll") for (int _i = 0; _i < 2; ++_i) \
;         __builtin_amdgcn_global_load_lds((const unsigned*)((const char*)(gbase) + (voff)[_i]), (LAS unsigned*)(lds + (bufoff) + ldsw + _i * 8192), 16, 0, 0); } while (0)
; #define PG8_LDA(dst, b, h) do { _Pragma("unroll") for (int m = 0; m < 4; ++m) _Pragma("unroll") for (int k = 0; k < 2; ++k) dst[m][k] = *(const LAS bf16x8*)(lds + PG8_SA(b, h) + aoff + m * 2048 + k * 1024); } while (0)
; #define PG8_LDB(dst, b, h) do { _Pragma("unroll") for (int n = 0; n < 2; ++n) _Pragma("unroll") for (int k = 0; k < 2; ++k) dst[n][k] = *(const LAS bf16x8*)(lds + PG8_SB(b, h) + boff + n * 2048 + k * 1024); } while (0)
; #define PG8_MMA(ai, bj, At, Bt) do { __builtin_amdgcn_s_setprio(1); _Pragma("unroll") for (int m = 0; m < 4; ++m) _Pragma("unroll") for (int n = 0; n < 2; ++n) _Pragma("unroll") for (int k = 0; k < 2; ++k) \
;         acc[ai][bj][m][n] = __builtin_amdgcn_mfma_f32_16x16x32_bf16(Bt[n][k], At[m][k], acc[ai][bj][m][n], 0, 0, 0); __builtin_amdgcn_s_setprio(0); } while (0)
; #define PG8_WAIT_V(n) asm volatile("s_waitcnt vmcnt(" #n ")" ::: "memory")
; #define PG8_WAIT_L(n) asm volatile("s_waitcnt lgkmcnt(" #n ")" ::: "memory")
; template <class Epi, class Sched, bool ALIGN_EPI = false, bool SP2 = false>
; __device__ __forceinline__ void gemm_phase(LAS unsigned char* lds, const Gemm g, const Sched& S, const Epi& E) {
;     ...
;         for (int t = 0; t < nt; t += 2) {
;             const bool last = (t == nt - 2);
;             const char* a1 = cA + (size_t)(t + 1) * kstep;
;             const char* a2 = last ? nA : cA + (size_t)(t + 2) * kstep; const char* b2 = last ? nB : cB + (size_t)(t + 2) * kstep;
;             const char* a3 = a2 + kstep; const char* b3 = b2 + kstep;
;             if (last && has_next) S.a_ready(nxt);
;             if constexpr (SP2) {
;             PG8_LDB(B0, 0, 0); PG8_LDB(B1, 0, 1); PG8_SCHED; PG8_LDA(At, 0, 0); PG8_STAGE(PG8_SA(1, 1), a1 + hstep, voffA);
;             PG8_WAIT_V(8); PG8_WAIT_L(0); PG8_BAR; PG8_MMA(0, 0, At, B0); PG8_MMA(0, 1, At, B1); PG8_BAR; PG8_SCHED;
;             PG8_LDA(At, 0, 1); PG8_STAGE(PG8_SB(0, 0), b2, voffB); PG8_STAGE(PG8_SB(0, 1), b2 + hstep, voffB); PG8_STAGE(PG8_SA(0, 0), a2, voffA);
;             PG8_WAIT_V(8); PG8_WAIT_L(0); PG8_BAR; PG8_MMA(1, 0, At, B0); PG8_MMA(1, 1, At, B1); PG8_BAR; PG8_SCHED;
.LBB0_924:
	s_add_u32 s28, s26, 0xfff80080
	s_addc_u32 s29, s27, -1
	s_add_i32 s51, 0, 0x10000
	s_cmp_eq_u32 s50, 28
	s_cselect_b32 s31, s7, s29
	s_cselect_b32 s30, s8, s28
	v_add_u32_e32 v148, s51, v151
	s_cselect_b32 s29, s19, s49
	s_cselect_b32 s28, s21, s35
	s_add_i32 s54, 0, 0x14000
	ds_read_b128 v[140:143], v148
	ds_read_b128 v[144:147], v148 offset:1024
	ds_read_b128 v[156:159], v148 offset:2048
	ds_read_b128 v[160:163], v148 offset:3072
	v_add_u32_e32 v148, s54, v151
	ds_read_b128 v[164:167], v148
	ds_read_b128 v[168:171], v148 offset:1024
	ds_read_b128 v[172:175], v148 offset:2048
	ds_read_b128 v[176:179], v148 offset:3072
	v_lshl_add_u64 v[212:213], s[26:27], 0, v[136:137]
	s_add_i32 m0, s42, 0xc000
	ds_read_b128 v[180:183], v155
	ds_read_b128 v[184:187], v155 offset:1024
	ds_read_b128 v[188:191], v155 offset:2048
	ds_read_b128 v[192:195], v155 offset:3072
	ds_read_b128 v[196:199], v155 offset:4096
	ds_read_b128 v[200:203], v155 offset:5120
	ds_read_b128 v[204:207], v155 offset:6144
	ds_read_b128 v[208:211], v155 offset:7168
	global_load_lds_dwordx4 v[212:213], off
	v_lshl_add_u64 v[212:213], s[26:27], 0, v[138:139]
	s_add_i32 m0, s42, 0xe000
	s_nop 0
	global_load_lds_dwordx4 v[212:213], off
	s_waitcnt vmcnt(8)
	s_waitcnt lgkmcnt(0)
	s_barrier
	s_setprio 1
	s_waitcnt lgkmcnt(0)
	v_mfma_f32_16x16x32_bf16 v[126:129], v[140:143], v[180:183], v[126:129]
	v_mfma_f32_16x16x32_bf16 v[122:125], v[156:159], v[180:183], v[122:125]
	v_mfma_f32_16x16x32_bf16 v[106:109], v[156:159], v[188:191], v[106:109]
	v_mfma_f32_16x16x32_bf16 v[110:113], v[140:143], v[188:191], v[110:113]
	v_mfma_f32_16x16x32_bf16 v[94:97], v[140:143], v[196:199], v[94:97]
	v_mfma_f32_16x16x32_bf16 v[90:93], v[156:159], v[196:199], v[90:93]
	v_mfma_f32_16x16x32_bf16 v[74:77], v[156:159], v[204:207], v[74:77]
	v_mfma_f32_16x16x32_bf16 v[78:81], v[140:143], v[204:207], v[78:81]
	v_mfma_f32_16x16x32_bf16 v[126:129], v[144:147], v[184:187], v[126:129]
	v_mfma_f32_16x16x32_bf16 v[122:125], v[160:163], v[184:187], v[122:125]
	v_mfma_f32_16x16x32_bf16 v[106:109], v[160:163], v[192:195], v[106:109]
	v_mfma_f32_16x16x32_bf16 v[110:113], v[144:147], v[192:195], v[110:113]
	v_mfma_f32_16x16x32_bf16 v[94:97], v[144:147], v[200:203], v[94:97]
	v_mfma_f32_16x16x32_bf16 v[90:93], v[160:163], v[200:203], v[90:93]
	v_mfma_f32_16x16x32_bf16 v[74:77], v[160:163], v[208:211], v[74:77]
	v_mfma_f32_16x16x32_bf16 v[78:81], v[144:147], v[208:211], v[78:81]
	s_setprio 0
	s_setprio 1
	v_mfma_f32_16x16x32_bf16 v[118:121], v[164:167], v[180:183], v[118:121]
	v_mfma_f32_16x16x32_bf16 v[114:117], v[172:175], v[180:183], v[114:117]
	v_mfma_f32_16x16x32_bf16 v[98:101], v[172:175], v[188:191], v[98:101]
	v_mfma_f32_16x16x32_bf16 v[102:105], v[164:167], v[188:191], v[102:105]
	v_mfma_f32_16x16x32_bf16 v[86:89], v[164:167], v[196:199], v[86:89]
	v_mfma_f32_16x16x32_bf16 v[82:85], v[172:175], v[196:199], v[82:85]
	v_mfma_f32_16x16x32_bf16 v[66:69], v[172:175], v[204:207], v[66:69]
	v_mfma_f32_16x16x32_bf16 v[70:73], v[164:167], v[204:207], v[70:73]
	v_mfma_f32_16x16x32_bf16 v[118:121], v[168:171], v[184:187], v[118:121]
	v_mfma_f32_16x16x32_bf16 v[114:117], v[176:179], v[184:187], v[114:117]
	v_mfma_f32_16x16x32_bf16 v[98:101], v[176:179], v[192:195], v[98:101]
	v_mfma_f32_16x16x32_bf16 v[102:105], v[168:171], v[192:195], v[102:105]
	v_mfma_f32_16x16x32_bf16 v[86:89], v[168:171], v[200:203], v[86:89]
	v_mfma_f32_16x16x32_bf16 v[82:85], v[176:179], v[200:203], v[82:85]
	v_mfma_f32_16x16x32_bf16 v[66:69], v[176:179], v[208:211], v[66:69]
	v_mfma_f32_16x16x32_bf16 v[70:73], v[168:171], v[208:211], v[70:73]
	s_setprio 0
	s_barrier
	s_add_i32 s51, s51, s41
	v_lshl_add_u64 v[212:213], s[28:29], 0, v[0:1]
	s_mov_b32 m0, s51
	ds_read_b128 v[180:183], v155 offset:16384
	ds_read_b128 v[184:187], v155 offset:17408
	ds_read_b128 v[188:191], v155 offset:18432
	ds_read_b128 v[192:195], v155 offset:19456
	ds_read_b128 v[196:199], v155 offset:20480
	ds_read_b128 v[200:203], v155 offset:21504
	ds_read_b128 v[204:207], v155 offset:22528
	ds_read_b128 v[208:211], v155 offset:23552
	global_load_lds_dwordx4 v[212:213], off
	s_add_i32 m0, s51, 0x2000
	s_add_u32 s52, s28, 0x80000
	v_lshl_add_u64 v[214:215], s[28:29], 0, v[130:131]
	s_addc_u32 s53, s29, 0
	s_add_i32 s51, s54, s41
	global_load_lds_dwordx4 v[214:215], off
	v_lshl_add_u64 v[216:217], s[52:53], 0, v[0:1]
	s_mov_b32 m0, s51
	v_lshl_add_u64 v[218:219], s[30:31], 0, v[132:133]
	global_load_lds_dwordx4 v[216:217], off
	v_lshl_add_u64 v[216:217], s[52:53], 0, v[130:131]
	s_add_i32 m0, s51, 0x2000
	s_nop 0
	global_load_lds_dwordx4 v[216:217], off
	v_lshl_add_u64 v[216:217], s[30:31], 0, v[134:135]
	s_mov_b32 m0, s42
	s_nop 0
	global_load_lds_dwordx4 v[216:217], off
	s_mov_b32 m0, s43
	s_nop 0
	global_load_lds_dwordx4 v[218:219], off
	s_waitcnt vmcnt(8)
	s_waitcnt lgkmcnt(0)
	s_barrier
; #define PG8_STAGE(bufoff, gbase, voff) do { _Pragma("unroll") for (int _i = 0; _i < 2; ++_i) \
;         __builtin_amdgcn_global_load_lds((const unsigned*)((const char*)(gbase) + (voff)[_i]), (LAS unsigned*)(lds + (bufoff) + ldsw + _i * 8192), 16, 0, 0); } while (0)
; #define PG8_LDA(dst, b, h) do { _Pragma("unroll") for (int m = 0; m < 4; ++m) _Pragma("unroll") for (int k = 0; k < 2; ++k) dst[m][k] = *(const LAS bf16x8*)(lds + PG8_SA(b, h) + aoff + m * 2048 + k * 1024); } while (0)
; #define PG8_LDB(dst, b, h) do { _Pragma("unroll") for (int n = 0; n < 2; ++n) _Pragma("unroll") for (int k = 0; k < 2; ++k) dst[n][k] = *(const LAS bf16x8*)(lds + PG8_SB(b, h) + boff + n * 2048 + k * 1024); } while (0)
; #define PG8_MMA(ai, bj, At, Bt) do { __builtin_amdgcn_s_setprio(1); _Pragma("unroll") for (int m = 0; m < 4; ++m) _Pragma("unroll") for (int n = 0; n < 2; ++n) _Pragma("unroll") for (int k = 0; k < 2; ++k) \
;         acc[ai][bj][m][n] = __builtin_amdgcn_mfma_f32_16x16x32_bf16(Bt[n][k], At[m][k], acc[ai][bj][m][n], 0, 0, 0); __builtin_amdgcn_s_setprio(0); } while (0)
; #define PG8_WAIT_V(n) asm volatile("s_waitcnt vmcnt(" #n ")" ::: "memory")
; #define PG8_WAIT_L(n) asm volatile("s_waitcnt lgkmcnt(" #n ")" ::: "memory")
; #define PG8_BAR __builtin_amdgcn_s_barrier()
; #define PG8_SCHED __builtin_amdgcn_sched_barrier(0)
; template <class Epi, class Sched, bool ALIGN_EPI = false, bool SP2 = false>
; __device__ __forceinline__ void gemm_phase(LAS unsigned char* lds, const Gemm g, const Sched& S, const Epi& E) {
;     ...
;             PG8_WAIT_V(8); PG8_WAIT_L(0); PG8_BAR; PG8_MMA(1, 0, At, B0); PG8_MMA(1, 1, At, B1); PG8_BAR; PG8_SCHED;
;             PG8_LDB(B0, 1, 0); PG8_LDB(B1, 1, 1); PG8_SCHED; PG8_LDA(At, 1, 0); PG8_STAGE(PG8_SA(0, 1), a2 + hstep, voffA);
;             PG8_WAIT_V(8); PG8_WAIT_L(0); PG8_BAR; PG8_MMA(0, 0, At, B0); PG8_MMA(0, 1, At, B1); PG8_BAR; PG8_SCHED;
;             PG8_LDA(At, 1, 1); PG8_STAGE(PG8_SB(1, 0), b3, voffB); PG8_STAGE(PG8_SB(1, 1), b3 + hstep, voffB); PG8_STAGE(PG8_SA(1, 0), a3, voffA);
	s_setprio 1
	s_waitcnt lgkmcnt(0)
	v_mfma_f32_16x16x32_bf16 v[62:65], v[140:143], v[180:183], v[62:65]
	v_mfma_f32_16x16x32_bf16 v[58:61], v[156:159], v[180:183], v[58:61]
	v_mfma_f32_16x16x32_bf16 v[42:45], v[156:159], v[188:191], v[42:45]
	v_mfma_f32_16x16x32_bf16 v[46:49], v[140:143], v[188:191], v[46:49]
	v_mfma_f32_16x16x32_bf16 v[30:33], v[140:143], v[196:199], v[30:33]
	v_mfma_f32_16x16x32_bf16 v[26:29], v[156:159], v[196:199], v[26:29]
	v_mfma_f32_16x16x32_bf16 v[10:13], v[156:159], v[204:207], v[10:13]
	v_mfma_f32_16x16x32_bf16 v[14:17], v[140:143], v[204:207], v[14:17]
	v_mfma_f32_16x16x32_bf16 v[62:65], v[144:147], v[184:187], v[62:65]
	v_mfma_f32_16x16x32_bf16 v[58:61], v[160:163], v[184:187], v[58:61]
	v_mfma_f32_16x16x32_bf16 v[42:45], v[160:163], v[192:195], v[42:45]
	v_mfma_f32_16x16x32_bf16 v[46:49], v[144:147], v[192:195], v[46:49]
	v_mfma_f32_16x16x32_bf16 v[30:33], v[144:147], v[200:203], v[30:33]
	v_mfma_f32_16x16x32_bf16 v[26:29], v[160:163], v[200:203], v[26:29]
	v_mfma_f32_16x16x32_bf16 v[10:13], v[160:163], v[208:211], v[10:13]
	v_mfma_f32_16x16x32_bf16 v[14:17], v[144:147], v[208:211], v[14:17]
	s_setprio 0
	s_setprio 1
	v_mfma_f32_16x16x32_bf16 v[54:57], v[164:167], v[180:183], v[54:57]
	v_mfma_f32_16x16x32_bf16 v[50:53], v[172:175], v[180:183], v[50:53]
	v_mfma_f32_16x16x32_bf16 v[34:37], v[172:175], v[188:191], v[34:37]
	v_mfma_f32_16x16x32_bf16 v[38:41], v[164:167], v[188:191], v[38:41]
	v_mfma_f32_16x16x32_bf16 v[22:25], v[164:167], v[196:199], v[22:25]
	v_mfma_f32_16x16x32_bf16 v[18:21], v[172:175], v[196:199], v[18:21]
	v_mfma_f32_16x16x32_bf16 v[2:5], v[172:175], v[204:207], v[2:5]
	v_mfma_f32_16x16x32_bf16 v[6:9], v[164:167], v[204:207], v[6:9]
	v_mfma_f32_16x16x32_bf16 v[54:57], v[168:171], v[184:187], v[54:57]
	v_mfma_f32_16x16x32_bf16 v[50:53], v[176:179], v[184:187], v[50:53]
	v_mfma_f32_16x16x32_bf16 v[34:37], v[176:179], v[192:195], v[34:37]
	v_mfma_f32_16x16x32_bf16 v[38:41], v[168:171], v[192:195], v[38:41]
	v_mfma_f32_16x16x32_bf16 v[22:25], v[168:171], v[200:203], v[22:25]
	v_mfma_f32_16x16x32_bf16 v[18:21], v[176:179], v[200:203], v[18:21]
	v_mfma_f32_16x16x32_bf16 v[2:5], v[176:179], v[208:211], v[2:5]
	v_mfma_f32_16x16x32_bf16 v[6:9], v[168:171], v[208:211], v[6:9]
	s_setprio 0
	s_barrier
	s_add_i32 s51, 0, 0x18000
	v_add_u32_e32 v148, s51, v151
	s_add_i32 s52, 0, 0x1c000
	ds_read_b128 v[140:143], v148
	ds_read_b128 v[144:147], v148 offset:1024
	ds_read_b128 v[156:159], v148 offset:2048
	ds_read_b128 v[160:163], v148 offset:3072
	v_add_u32_e32 v148, s52, v151
	ds_read_b128 v[164:167], v148
	ds_read_b128 v[168:171], v148 offset:1024
	ds_read_b128 v[172:175], v148 offset:2048
	ds_read_b128 v[176:179], v148 offset:3072
	s_add_u32 s30, s30, 0x80000
	s_addc_u32 s31, s31, 0
	s_mov_b32 m0, s44
	v_lshl_add_u64 v[220:221], s[30:31], 0, v[134:135]
	ds_read_b128 v[180:183], v155 offset:32768
	ds_read_b128 v[184:187], v155 offset:33792
	ds_read_b128 v[188:191], v155 offset:34816
	ds_read_b128 v[192:195], v155 offset:35840
	ds_read_b128 v[196:199], v155 offset:36864
	ds_read_b128 v[200:203], v155 offset:37888
	ds_read_b128 v[204:207], v155 offset:38912
	ds_read_b128 v[208:211], v155 offset:39936
	global_load_lds_dwordx4 v[220:221], off
	v_lshl_add_u64 v[220:221], s[30:31], 0, v[132:133]
	s_mov_b32 m0, s45
	s_nop 0
	global_load_lds_dwordx4 v[220:221], off
	s_waitcnt vmcnt(8)
	s_waitcnt lgkmcnt(0)
	s_barrier
	s_setprio 1
	s_waitcnt lgkmcnt(0)
	v_mfma_f32_16x16x32_bf16 v[126:129], v[140:143], v[180:183], v[126:129]
	v_mfma_f32_16x16x32_bf16 v[122:125], v[156:159], v[180:183], v[122:125]
	v_mfma_f32_16x16x32_bf16 v[106:109], v[156:159], v[188:191], v[106:109]
	v_mfma_f32_16x16x32_bf16 v[110:113], v[140:143], v[188:191], v[110:113]
	v_mfma_f32_16x16x32_bf16 v[94:97], v[140:143], v[196:199], v[94:97]
	v_mfma_f32_16x16x32_bf16 v[90:93], v[156:159], v[196:199], v[90:93]
	v_mfma_f32_16x16x32_bf16 v[74:77], v[156:159], v[204:207], v[74:77]
	v_mfma_f32_16x16x32_bf16 v[78:81], v[140:143], v[204:207], v[78:81]
	v_mfma_f32_16x16x32_bf16 v[126:129], v[144:147], v[184:187], v[126:129]
	v_mfma_f32_16x16x32_bf16 v[122:125], v[160:163], v[184:187], v[122:125]
	v_mfma_f32_16x16x32_bf16 v[106:109], v[160:163], v[192:195], v[106:109]
	v_mfma_f32_16x16x32_bf16 v[110:113], v[144:147], v[192:195], v[110:113]
	v_mfma_f32_16x16x32_bf16 v[94:97], v[144:147], v[200:203], v[94:97]
	v_mfma_f32_16x16x32_bf16 v[90:93], v[160:163], v[200:203], v[90:93]
	v_mfma_f32_16x16x32_bf16 v[74:77], v[160:163], v[208:211], v[74:77]
	v_mfma_f32_16x16x32_bf16 v[78:81], v[144:147], v[208:211], v[78:81]
	s_setprio 0
	s_setprio 1
	v_mfma_f32_16x16x32_bf16 v[118:121], v[164:167], v[180:183], v[118:121]
	v_mfma_f32_16x16x32_bf16 v[114:117], v[172:175], v[180:183], v[114:117]
	v_mfma_f32_16x16x32_bf16 v[98:101], v[172:175], v[188:191], v[98:101]
	v_mfma_f32_16x16x32_bf16 v[102:105], v[164:167], v[188:191], v[102:105]
	v_mfma_f32_16x16x32_bf16 v[86:89], v[164:167], v[196:199], v[86:89]
	v_mfma_f32_16x16x32_bf16 v[82:85], v[172:175], v[196:199], v[82:85]
	v_mfma_f32_16x16x32_bf16 v[66:69], v[172:175], v[204:207], v[66:69]
	v_mfma_f32_16x16x32_bf16 v[70:73], v[164:167], v[204:207], v[70:73]
	v_mfma_f32_16x16x32_bf16 v[118:121], v[168:171], v[184:187], v[118:121]
	v_mfma_f32_16x16x32_bf16 v[114:117], v[176:179], v[184:187], v[114:117]
	v_mfma_f32_16x16x32_bf16 v[98:101], v[176:179], v[192:195], v[98:101]
	v_mfma_f32_16x16x32_bf16 v[102:105], v[168:171], v[192:195], v[102:105]
	v_mfma_f32_16x16x32_bf16 v[86:89], v[168:171], v[200:203], v[86:89]
	v_mfma_f32_16x16x32_bf16 v[82:85], v[176:179], v[200:203], v[82:85]
	v_mfma_f32_16x16x32_bf16 v[66:69], v[176:179], v[208:211], v[66:69]
	v_mfma_f32_16x16x32_bf16 v[70:73], v[168:171], v[208:211], v[70:73]
	s_setprio 0
	s_barrier
; #define PG8_STAGE(bufoff, gbase, voff) do { _Pragma("unroll") for (int _i = 0; _i < 2; ++_i) \
;         __builtin_amdgcn_global_load_lds((const unsigned*)((const char*)(gbase) + (voff)[_i]), (LAS unsigned*)(lds + (bufoff) + ldsw + _i * 8192), 16, 0, 0); } while (0)
; #define PG8_LDA(dst, b, h) do { _Pragma("unroll") for (int m = 0; m < 4; ++m) _Pragma("unroll") for (int k = 0; k < 2; ++k) dst[m][k] = *(const LAS bf16x8*)(lds + PG8_SA(b, h) + aoff + m * 2048 + k * 1024); } while (0)
; #define PG8_MMA(ai, bj, At, Bt) do { __builtin_amdgcn_s_setprio(1); _Pragma("unroll") for (int m = 0; m < 4; ++m) _Pragma("unroll") for (int n = 0; n < 2; ++n) _Pragma("unroll") for (int k = 0; k < 2; ++k) \
;         acc[ai][bj][m][n] = __builtin_amdgcn_mfma_f32_16x16x32_bf16(Bt[n][k], At[m][k], acc[ai][bj][m][n], 0, 0, 0); __builtin_amdgcn_s_setprio(0); } while (0)
; #define PG8_WAIT_V(n) asm volatile("s_waitcnt vmcnt(" #n ")" ::: "memory")
; #define PG8_WAIT_L(n) asm volatile("s_waitcnt lgkmcnt(" #n ")" ::: "memory")
; #define PG8_BAR __builtin_amdgcn_s_barrier()
; #define PG8_SCHED __builtin_amdgcn_sched_barrier(0)
; template <class Epi, class Sched, bool ALIGN_EPI = false, bool SP2 = false>
; __device__ __forceinline__ void gemm_phase(LAS unsigned char* lds, const Gemm g, const Sched& S, const Epi& E) {
;     ...
;             PG8_LDA(At, 1, 1); PG8_STAGE(PG8_SB(1, 0), b3, voffB); PG8_STAGE(PG8_SB(1, 1), b3 + hstep, voffB); PG8_STAGE(PG8_SA(1, 0), a3, voffA);
;             PG8_WAIT_V(8); PG8_WAIT_L(0); PG8_BAR; PG8_MMA(1, 0, At, B0); PG8_MMA(1, 1, At, B1); PG8_BAR; PG8_SCHED;
;     ...
;         if constexpr (ALIGN_EPI) { if (wr == 0) PG8_BAR; }
	s_add_i32 s30, s51, s41
	v_lshl_add_u64 v[212:213], v[212:213], 0, s[12:13]
	s_mov_b32 m0, s30
	ds_read_b128 v[180:183], v155 offset:49152
	ds_read_b128 v[184:187], v155 offset:50176
	ds_read_b128 v[188:191], v155 offset:51200
	ds_read_b128 v[192:195], v155 offset:52224
	ds_read_b128 v[196:199], v155 offset:53248
	ds_read_b128 v[200:203], v155 offset:54272
	ds_read_b128 v[204:207], v155 offset:55296
	ds_read_b128 v[208:211], v155 offset:56320
	global_load_lds_dwordx4 v[212:213], off
	s_add_i32 m0, s30, 0x2000
	s_add_u32 s28, s28, 0x80080
	v_lshl_add_u64 v[212:213], v[214:215], 0, s[12:13]
	s_addc_u32 s29, s29, 0
	s_add_i32 s30, s52, s41
	global_load_lds_dwordx4 v[212:213], off
	v_lshl_add_u64 v[212:213], s[28:29], 0, v[0:1]
	s_mov_b32 m0, s30
	s_nop 0
	global_load_lds_dwordx4 v[212:213], off
	v_lshl_add_u64 v[212:213], s[28:29], 0, v[130:131]
	s_add_i32 m0, s30, 0x2000
	s_nop 0
	global_load_lds_dwordx4 v[212:213], off
	v_lshl_add_u64 v[212:213], v[216:217], 0, s[12:13]
	s_mov_b32 m0, s46
	s_nop 0
	global_load_lds_dwordx4 v[212:213], off
	v_lshl_add_u64 v[212:213], v[218:219], 0, s[12:13]
	s_mov_b32 m0, s47
	s_nop 0
	global_load_lds_dwordx4 v[212:213], off
	s_waitcnt vmcnt(8)
	s_waitcnt lgkmcnt(0)
	s_barrier
	s_setprio 1
	s_waitcnt lgkmcnt(0)
	v_mfma_f32_16x16x32_bf16 v[62:65], v[140:143], v[180:183], v[62:65]
	v_mfma_f32_16x16x32_bf16 v[58:61], v[156:159], v[180:183], v[58:61]
	v_mfma_f32_16x16x32_bf16 v[42:45], v[156:159], v[188:191], v[42:45]
	v_mfma_f32_16x16x32_bf16 v[46:49], v[140:143], v[188:191], v[46:49]
	v_mfma_f32_16x16x32_bf16 v[30:33], v[140:143], v[196:199], v[30:33]
	v_mfma_f32_16x16x32_bf16 v[26:29], v[156:159], v[196:199], v[26:29]
	v_mfma_f32_16x16x32_bf16 v[10:13], v[156:159], v[204:207], v[10:13]
	v_mfma_f32_16x16x32_bf16 v[14:17], v[140:143], v[204:207], v[14:17]
	v_mfma_f32_16x16x32_bf16 v[62:65], v[144:147], v[184:187], v[62:65]
	v_mfma_f32_16x16x32_bf16 v[58:61], v[160:163], v[184:187], v[58:61]
	v_mfma_f32_16x16x32_bf16 v[42:45], v[160:163], v[192:195], v[42:45]
	v_mfma_f32_16x16x32_bf16 v[46:49], v[144:147], v[192:195], v[46:49]
	v_mfma_f32_16x16x32_bf16 v[30:33], v[144:147], v[200:203], v[30:33]
	v_mfma_f32_16x16x32_bf16 v[26:29], v[160:163], v[200:203], v[26:29]
	v_mfma_f32_16x16x32_bf16 v[10:13], v[160:163], v[208:211], v[10:13]
	v_mfma_f32_16x16x32_bf16 v[14:17], v[144:147], v[208:211], v[14:17]
	s_setprio 0
	s_setprio 1
	v_mfma_f32_16x16x32_bf16 v[54:57], v[164:167], v[180:183], v[54:57]
	v_mfma_f32_16x16x32_bf16 v[50:53], v[172:175], v[180:183], v[50:53]
	v_mfma_f32_16x16x32_bf16 v[34:37], v[172:175], v[188:191], v[34:37]
	v_mfma_f32_16x16x32_bf16 v[38:41], v[164:167], v[188:191], v[38:41]
	v_mfma_f32_16x16x32_bf16 v[22:25], v[164:167], v[196:199], v[22:25]
	v_mfma_f32_16x16x32_bf16 v[18:21], v[172:175], v[196:199], v[18:21]
	v_mfma_f32_16x16x32_bf16 v[2:5], v[172:175], v[204:207], v[2:5]
	v_mfma_f32_16x16x32_bf16 v[6:9], v[164:167], v[204:207], v[6:9]
	v_mfma_f32_16x16x32_bf16 v[54:57], v[168:171], v[184:187], v[54:57]
	v_mfma_f32_16x16x32_bf16 v[50:53], v[176:179], v[184:187], v[50:53]
	v_mfma_f32_16x16x32_bf16 v[34:37], v[176:179], v[192:195], v[34:37]
	v_mfma_f32_16x16x32_bf16 v[38:41], v[168:171], v[192:195], v[38:41]
	v_mfma_f32_16x16x32_bf16 v[22:25], v[168:171], v[200:203], v[22:25]
	v_mfma_f32_16x16x32_bf16 v[18:21], v[176:179], v[200:203], v[18:21]
	v_mfma_f32_16x16x32_bf16 v[2:5], v[176:179], v[208:211], v[2:5]
	v_mfma_f32_16x16x32_bf16 v[6:9], v[168:171], v[208:211], v[6:9]
	s_setprio 0
	s_barrier
	s_add_i32 s50, s50, 2
	s_add_u32 s26, s26, 0x100
	s_addc_u32 s27, s27, 0
	s_add_u32 s35, s35, 0x100
	s_addc_u32 s49, s49, 0
	s_cmp_gt_u32 s50, 29
	s_cbranch_scc0 .LBB0_924
	s_and_b64 vcc, exec, s[16:17]
	s_cbranch_vccz .LBB0_927
	s_barrier

; #define PG8_STAGE(bufoff, gbase, voff) do { _Pragma("unroll") for (int _i = 0; _i < 2; ++_i) \
;         __builtin_amdgcn_global_load_lds((const unsigned*)((const char*)(gbase) + (voff)[_i]), (LAS unsigned*)(lds + (bufoff) + ldsw + _i * 8192), 16, 0, 0); } while (0)
; #define PG8_LDA(dst, b, h) do { _Pragma("unroll") for (int m = 0; m < 4; ++m) _Pragma("unroll") for (int k = 0; k < 2; ++k) dst[m][k] = *(const LAS bf16x8*)(lds + PG8_SA(b, h) + aoff + m * 2048 + k * 1024); } while (0)
; #define PG8_LDB(dst, b, h) do { _Pragma("unroll") for (int n = 0; n < 2; ++n) _Pragma("unroll") for (int k = 0; k < 2; ++k) dst[n][k] = *(const LAS bf16x8*)(lds + PG8_SB(b, h) + boff + n * 2048 + k * 1024); } while (0)
; #define PG8_MMA(ai, bj, At, Bt) do { __builtin_amdgcn_s_setprio(1); _Pragma("unroll") for (int m = 0; m < 4; ++m) _Pragma("unroll") for (int n = 0; n < 2; ++n) _Pragma("unroll") for (int k = 0; k < 2; ++k) \
;         acc[ai][bj][m][n] = __builtin_amdgcn_mfma_f32_16x16x32_bf16(Bt[n][k], At[m][k], acc[ai][bj][m][n], 0, 0, 0); __builtin_amdgcn_s_setprio(0); } while (0)
; #define PG8_WAIT_V(n) asm volatile("s_waitcnt vmcnt(" #n ")" ::: "memory")
; #define PG8_WAIT_L(n) asm volatile("s_waitcnt lgkmcnt(" #n ")" ::: "memory")
; template <class Epi, class Sched, bool ALIGN_EPI = false, bool SP2 = false>
; __device__ __forceinline__ void gemm_phase(LAS unsigned char* lds, const Gemm g, const Sched& S, const Epi& E) {
;     ...
;         for (int t = 0; t < nt; t += 2) {
;             const bool last = (t == nt - 2);
;             const char* a1 = cA + (size_t)(t + 1) * kstep;
;             const char* a2 = last ? nA : cA + (size_t)(t + 2) * kstep; const char* b2 = last ? nB : cB + (size_t)(t + 2) * kstep;
;             const char* a3 = a2 + kstep; const char* b3 = b2 + kstep;
;             if (last && has_next) S.a_ready(nxt);
;             if constexpr (SP2) {
;             PG8_LDB(B0, 0, 0); PG8_LDB(B1, 0, 1); PG8_SCHED; PG8_LDA(At, 0, 0); PG8_STAGE(PG8_SA(1, 1), a1 + hstep, voffA);
;             PG8_WAIT_V(8); PG8_WAIT_L(0); PG8_BAR; PG8_MMA(0, 0, At, B0); PG8_MMA(0, 1, At, B1); PG8_BAR; PG8_SCHED;
;             PG8_LDA(At, 0, 1); PG8_STAGE(PG8_SB(0, 0), b2, voffB); PG8_STAGE(PG8_SB(0, 1), b2 + hstep, voffB); PG8_STAGE(PG8_SA(0, 0), a2, voffA);
;             PG8_WAIT_V(8); PG8_WAIT_L(0); PG8_BAR; PG8_MMA(1, 0, At, B0); PG8_MMA(1, 1, At, B1); PG8_BAR; PG8_SCHED;
.LBB0_1007:
	s_add_u32 s24, s22, 0x100
	s_addc_u32 s25, s23, 0
	s_add_i32 s49, 0, 0x10000
	s_cmpk_eq_i32 s48, 0x54
	s_cselect_b32 s29, s1, s25
	s_cselect_b32 s28, s0, s24
	s_cselect_b32 s27, s21, s47
	s_cselect_b32 s26, s20, s46
	s_add_i32 s50, 0, 0x14000
	v_add_u32_e32 v126, s49, v247
	v_add_u32_e32 v158, s50, v247
	ds_read_b128 v[90:93], v126
	ds_read_b128 v[102:105], v126 offset:1024
	ds_read_b128 v[114:117], v126 offset:2048
	ds_read_b128 v[126:129], v126 offset:3072
	ds_read_b128 v[138:141], v158
	ds_read_b128 v[142:145], v158 offset:1024
	ds_read_b128 v[154:157], v158 offset:2048
	ds_read_b128 v[158:161], v158 offset:3072
	v_lshl_add_u64 v[204:205], s[22:23], 0, v[200:201]
	s_add_i32 m0, s8, 0xc000
	ds_read_b128 v[162:165], v249
	ds_read_b128 v[166:169], v249 offset:1024
	ds_read_b128 v[170:173], v249 offset:2048
	ds_read_b128 v[174:177], v249 offset:3072
	ds_read_b128 v[178:181], v249 offset:4096
	ds_read_b128 v[182:185], v249 offset:5120
	ds_read_b128 v[186:189], v249 offset:6144
	ds_read_b128 v[190:193], v249 offset:7168
	global_load_lds_dwordx4 v[204:205], off
	v_lshl_add_u64 v[204:205], s[22:23], 0, v[202:203]
	s_add_i32 m0, s8, 0xe000
	s_nop 0
	global_load_lds_dwordx4 v[204:205], off
	s_waitcnt vmcnt(8)
	s_waitcnt lgkmcnt(0)
	s_barrier
	s_setprio 1
	s_waitcnt lgkmcnt(0)
	v_mfma_f32_16x16x32_bf16 v[150:153], v[90:93], v[162:165], v[150:153]
	v_mfma_f32_16x16x32_bf16 v[146:149], v[114:117], v[162:165], v[146:149]
	v_mfma_f32_16x16x32_bf16 v[118:121], v[114:117], v[170:173], v[118:121]
	v_mfma_f32_16x16x32_bf16 v[122:125], v[90:93], v[170:173], v[122:125]
	v_mfma_f32_16x16x32_bf16 v[98:101], v[90:93], v[178:181], v[98:101]
	v_mfma_f32_16x16x32_bf16 v[94:97], v[114:117], v[178:181], v[94:97]
	v_mfma_f32_16x16x32_bf16 v[74:77], v[114:117], v[186:189], v[74:77]
	v_mfma_f32_16x16x32_bf16 v[78:81], v[90:93], v[186:189], v[78:81]
	v_mfma_f32_16x16x32_bf16 v[150:153], v[102:105], v[166:169], v[150:153]
	v_mfma_f32_16x16x32_bf16 v[146:149], v[126:129], v[166:169], v[146:149]
	v_mfma_f32_16x16x32_bf16 v[118:121], v[126:129], v[174:177], v[118:121]
	v_mfma_f32_16x16x32_bf16 v[122:125], v[102:105], v[174:177], v[122:125]
	v_mfma_f32_16x16x32_bf16 v[98:101], v[102:105], v[182:185], v[98:101]
	v_mfma_f32_16x16x32_bf16 v[94:97], v[126:129], v[182:185], v[94:97]
	v_mfma_f32_16x16x32_bf16 v[74:77], v[126:129], v[190:193], v[74:77]
	v_mfma_f32_16x16x32_bf16 v[78:81], v[102:105], v[190:193], v[78:81]
	s_setprio 0
	s_setprio 1
	v_mfma_f32_16x16x32_bf16 v[134:137], v[138:141], v[162:165], v[134:137]
	v_mfma_f32_16x16x32_bf16 v[130:133], v[154:157], v[162:165], v[130:133]
	v_mfma_f32_16x16x32_bf16 v[106:109], v[154:157], v[170:173], v[106:109]
	v_mfma_f32_16x16x32_bf16 v[110:113], v[138:141], v[170:173], v[110:113]
	v_mfma_f32_16x16x32_bf16 v[86:89], v[138:141], v[178:181], v[86:89]
	v_mfma_f32_16x16x32_bf16 v[82:85], v[154:157], v[178:181], v[82:85]
	v_mfma_f32_16x16x32_bf16 v[66:69], v[154:157], v[186:189], v[66:69]
	v_mfma_f32_16x16x32_bf16 v[70:73], v[138:141], v[186:189], v[70:73]
	v_mfma_f32_16x16x32_bf16 v[134:137], v[142:145], v[166:169], v[134:137]
	v_mfma_f32_16x16x32_bf16 v[130:133], v[158:161], v[166:169], v[130:133]
	v_mfma_f32_16x16x32_bf16 v[106:109], v[158:161], v[174:177], v[106:109]
	v_mfma_f32_16x16x32_bf16 v[110:113], v[142:145], v[174:177], v[110:113]
	v_mfma_f32_16x16x32_bf16 v[86:89], v[142:145], v[182:185], v[86:89]
	v_mfma_f32_16x16x32_bf16 v[82:85], v[158:161], v[182:185], v[82:85]
	v_mfma_f32_16x16x32_bf16 v[66:69], v[158:161], v[190:193], v[66:69]
	v_mfma_f32_16x16x32_bf16 v[70:73], v[142:145], v[190:193], v[70:73]
	s_setprio 0
	s_barrier
	s_add_i32 s22, s49, s7
	v_lshl_add_u64 v[204:205], s[26:27], 0, v[0:1]
	s_mov_b32 m0, s22
	ds_read_b128 v[162:165], v249 offset:16384
	ds_read_b128 v[166:169], v249 offset:17408
	ds_read_b128 v[170:173], v249 offset:18432
	ds_read_b128 v[174:177], v249 offset:19456
	ds_read_b128 v[178:181], v249 offset:20480
	ds_read_b128 v[182:185], v249 offset:21504
	ds_read_b128 v[186:189], v249 offset:22528
	ds_read_b128 v[190:193], v249 offset:23552
	global_load_lds_dwordx4 v[204:205], off
	s_add_i32 m0, s22, 0x2000
	s_add_u32 s22, s26, 0x160000
	v_lshl_add_u64 v[206:207], s[26:27], 0, v[194:195]
	s_addc_u32 s23, s27, 0
	s_add_i32 s49, s50, s7
	global_load_lds_dwordx4 v[206:207], off
	v_lshl_add_u64 v[208:209], s[22:23], 0, v[0:1]
	s_mov_b32 m0, s49
	v_lshl_add_u64 v[210:211], s[28:29], 0, v[196:197]
	global_load_lds_dwordx4 v[208:209], off
	v_lshl_add_u64 v[208:209], s[22:23], 0, v[194:195]
	s_add_i32 m0, s49, 0x2000
	s_nop 0
	global_load_lds_dwordx4 v[208:209], off
	v_lshl_add_u64 v[208:209], s[28:29], 0, v[198:199]
	s_mov_b32 m0, s8
	s_nop 0
	global_load_lds_dwordx4 v[208:209], off
	s_mov_b32 m0, s9
	s_nop 0
	global_load_lds_dwordx4 v[210:211], off
	s_waitcnt vmcnt(8)
	s_waitcnt lgkmcnt(0)
	s_barrier
; #define PG8_STAGE(bufoff, gbase, voff) do { _Pragma("unroll") for (int _i = 0; _i < 2; ++_i) \
;         __builtin_amdgcn_global_load_lds((const unsigned*)((const char*)(gbase) + (voff)[_i]), (LAS unsigned*)(lds + (bufoff) + ldsw + _i * 8192), 16, 0, 0); } while (0)
; #define PG8_LDA(dst, b, h) do { _Pragma("unroll") for (int m = 0; m < 4; ++m) _Pragma("unroll") for (int k = 0; k < 2; ++k) dst[m][k] = *(const LAS bf16x8*)(lds + PG8_SA(b, h) + aoff + m * 2048 + k * 1024); } while (0)
; #define PG8_LDB(dst, b, h) do { _Pragma("unroll") for (int n = 0; n < 2; ++n) _Pragma("unroll") for (int k = 0; k < 2; ++k) dst[n][k] = *(const LAS bf16x8*)(lds + PG8_SB(b, h) + boff + n * 2048 + k * 1024); } while (0)
; #define PG8_MMA(ai, bj, At, Bt) do { __builtin_amdgcn_s_setprio(1); _Pragma("unroll") for (int m = 0; m < 4; ++m) _Pragma("unroll") for (int n = 0; n < 2; ++n) _Pragma("unroll") for (int k = 0; k < 2; ++k) \
;         acc[ai][bj][m][n] = __builtin_amdgcn_mfma_f32_16x16x32_bf16(Bt[n][k], At[m][k], acc[ai][bj][m][n], 0, 0, 0); __builtin_amdgcn_s_setprio(0); } while (0)
; #define PG8_WAIT_V(n) asm volatile("s_waitcnt vmcnt(" #n ")" ::: "memory")
; #define PG8_WAIT_L(n) asm volatile("s_waitcnt lgkmcnt(" #n ")" ::: "memory")
; #define PG8_BAR __builtin_amdgcn_s_barrier()
; #define PG8_SCHED __builtin_amdgcn_sched_barrier(0)
; template <class Epi, class Sched, bool ALIGN_EPI = false, bool SP2 = false>
; __device__ __forceinline__ void gemm_phase(LAS unsigned char* lds, const Gemm g, const Sched& S, const Epi& E) {
;     ...
;             PG8_WAIT_V(8); PG8_WAIT_L(0); PG8_BAR; PG8_MMA(1, 0, At, B0); PG8_MMA(1, 1, At, B1); PG8_BAR; PG8_SCHED;
;             PG8_LDB(B0, 1, 0); PG8_LDB(B1, 1, 1); PG8_SCHED; PG8_LDA(At, 1, 0); PG8_STAGE(PG8_SA(0, 1), a2 + hstep, voffA);
;             PG8_WAIT_V(8); PG8_WAIT_L(0); PG8_BAR; PG8_MMA(0, 0, At, B0); PG8_MMA(0, 1, At, B1); PG8_BAR; PG8_SCHED;
;             PG8_LDA(At, 1, 1); PG8_STAGE(PG8_SB(1, 0), b3, voffB); PG8_STAGE(PG8_SB(1, 1), b3 + hstep, voffB); PG8_STAGE(PG8_SA(1, 0), a3, voffA);
	s_setprio 1
	s_waitcnt lgkmcnt(0)
	v_mfma_f32_16x16x32_bf16 v[62:65], v[90:93], v[162:165], v[62:65]
	v_mfma_f32_16x16x32_bf16 v[58:61], v[114:117], v[162:165], v[58:61]
	v_mfma_f32_16x16x32_bf16 v[42:45], v[114:117], v[170:173], v[42:45]
	v_mfma_f32_16x16x32_bf16 v[46:49], v[90:93], v[170:173], v[46:49]
	v_mfma_f32_16x16x32_bf16 v[30:33], v[90:93], v[178:181], v[30:33]
	v_mfma_f32_16x16x32_bf16 v[26:29], v[114:117], v[178:181], v[26:29]
	v_mfma_f32_16x16x32_bf16 v[10:13], v[114:117], v[186:189], v[10:13]
	v_mfma_f32_16x16x32_bf16 v[14:17], v[90:93], v[186:189], v[14:17]
	v_mfma_f32_16x16x32_bf16 v[62:65], v[102:105], v[166:169], v[62:65]
	v_mfma_f32_16x16x32_bf16 v[58:61], v[126:129], v[166:169], v[58:61]
	v_mfma_f32_16x16x32_bf16 v[42:45], v[126:129], v[174:177], v[42:45]
	v_mfma_f32_16x16x32_bf16 v[46:49], v[102:105], v[174:177], v[46:49]
	v_mfma_f32_16x16x32_bf16 v[30:33], v[102:105], v[182:185], v[30:33]
	v_mfma_f32_16x16x32_bf16 v[26:29], v[126:129], v[182:185], v[26:29]
	v_mfma_f32_16x16x32_bf16 v[10:13], v[126:129], v[190:193], v[10:13]
	v_mfma_f32_16x16x32_bf16 v[14:17], v[102:105], v[190:193], v[14:17]
	s_setprio 0
	s_setprio 1
	v_mfma_f32_16x16x32_bf16 v[54:57], v[138:141], v[162:165], v[54:57]
	v_mfma_f32_16x16x32_bf16 v[50:53], v[154:157], v[162:165], v[50:53]
	v_mfma_f32_16x16x32_bf16 v[34:37], v[154:157], v[170:173], v[34:37]
	v_mfma_f32_16x16x32_bf16 v[38:41], v[138:141], v[170:173], v[38:41]
	v_mfma_f32_16x16x32_bf16 v[22:25], v[138:141], v[178:181], v[22:25]
	v_mfma_f32_16x16x32_bf16 v[18:21], v[154:157], v[178:181], v[18:21]
	v_mfma_f32_16x16x32_bf16 v[2:5], v[154:157], v[186:189], v[2:5]
	v_mfma_f32_16x16x32_bf16 v[6:9], v[138:141], v[186:189], v[6:9]
	v_mfma_f32_16x16x32_bf16 v[54:57], v[142:145], v[166:169], v[54:57]
	v_mfma_f32_16x16x32_bf16 v[50:53], v[158:161], v[166:169], v[50:53]
	v_mfma_f32_16x16x32_bf16 v[34:37], v[158:161], v[174:177], v[34:37]
	v_mfma_f32_16x16x32_bf16 v[38:41], v[142:145], v[174:177], v[38:41]
	v_mfma_f32_16x16x32_bf16 v[22:25], v[142:145], v[182:185], v[22:25]
	v_mfma_f32_16x16x32_bf16 v[18:21], v[158:161], v[182:185], v[18:21]
	v_mfma_f32_16x16x32_bf16 v[2:5], v[158:161], v[190:193], v[2:5]
	v_mfma_f32_16x16x32_bf16 v[6:9], v[142:145], v[190:193], v[6:9]
	s_setprio 0
	s_barrier
	s_add_i32 s49, 0, 0x18000
	s_add_i32 s50, 0, 0x1c000
	v_add_u32_e32 v126, s49, v247
	v_add_u32_e32 v158, s50, v247
	ds_read_b128 v[90:93], v126
	ds_read_b128 v[102:105], v126 offset:1024
	ds_read_b128 v[114:117], v126 offset:2048
	ds_read_b128 v[126:129], v126 offset:3072
	ds_read_b128 v[138:141], v158
	ds_read_b128 v[142:145], v158 offset:1024
	ds_read_b128 v[154:157], v158 offset:2048
	ds_read_b128 v[158:161], v158 offset:3072
	s_add_u32 s22, s28, 0x160000
	s_addc_u32 s23, s29, 0
	s_mov_b32 m0, s30
	v_lshl_add_u64 v[212:213], s[22:23], 0, v[198:199]
	ds_read_b128 v[162:165], v249 offset:32768
	ds_read_b128 v[166:169], v249 offset:33792
	ds_read_b128 v[170:173], v249 offset:34816
	ds_read_b128 v[174:177], v249 offset:35840
	ds_read_b128 v[178:181], v249 offset:36864
	ds_read_b128 v[182:185], v249 offset:37888
	ds_read_b128 v[186:189], v249 offset:38912
	ds_read_b128 v[190:193], v249 offset:39936
	global_load_lds_dwordx4 v[212:213], off
	v_lshl_add_u64 v[212:213], s[22:23], 0, v[196:197]
	s_mov_b32 m0, s31
	s_nop 0
	global_load_lds_dwordx4 v[212:213], off
	s_waitcnt vmcnt(8)
	s_waitcnt lgkmcnt(0)
	s_barrier
	s_setprio 1
	s_waitcnt lgkmcnt(0)
	v_mfma_f32_16x16x32_bf16 v[150:153], v[90:93], v[162:165], v[150:153]
	v_mfma_f32_16x16x32_bf16 v[146:149], v[114:117], v[162:165], v[146:149]
	v_mfma_f32_16x16x32_bf16 v[118:121], v[114:117], v[170:173], v[118:121]
	v_mfma_f32_16x16x32_bf16 v[122:125], v[90:93], v[170:173], v[122:125]
	v_mfma_f32_16x16x32_bf16 v[98:101], v[90:93], v[178:181], v[98:101]
	v_mfma_f32_16x16x32_bf16 v[94:97], v[114:117], v[178:181], v[94:97]
	v_mfma_f32_16x16x32_bf16 v[74:77], v[114:117], v[186:189], v[74:77]
	v_mfma_f32_16x16x32_bf16 v[78:81], v[90:93], v[186:189], v[78:81]
	v_mfma_f32_16x16x32_bf16 v[150:153], v[102:105], v[166:169], v[150:153]
	v_mfma_f32_16x16x32_bf16 v[146:149], v[126:129], v[166:169], v[146:149]
	v_mfma_f32_16x16x32_bf16 v[118:121], v[126:129], v[174:177], v[118:121]
	v_mfma_f32_16x16x32_bf16 v[122:125], v[102:105], v[174:177], v[122:125]
	v_mfma_f32_16x16x32_bf16 v[98:101], v[102:105], v[182:185], v[98:101]
	v_mfma_f32_16x16x32_bf16 v[94:97], v[126:129], v[182:185], v[94:97]
	v_mfma_f32_16x16x32_bf16 v[74:77], v[126:129], v[190:193], v[74:77]
	v_mfma_f32_16x16x32_bf16 v[78:81], v[102:105], v[190:193], v[78:81]
	s_setprio 0
	s_setprio 1
	v_mfma_f32_16x16x32_bf16 v[134:137], v[138:141], v[162:165], v[134:137]
	v_mfma_f32_16x16x32_bf16 v[130:133], v[154:157], v[162:165], v[130:133]
	v_mfma_f32_16x16x32_bf16 v[106:109], v[154:157], v[170:173], v[106:109]
	v_mfma_f32_16x16x32_bf16 v[110:113], v[138:141], v[170:173], v[110:113]
	v_mfma_f32_16x16x32_bf16 v[86:89], v[138:141], v[178:181], v[86:89]
	v_mfma_f32_16x16x32_bf16 v[82:85], v[154:157], v[178:181], v[82:85]
	v_mfma_f32_16x16x32_bf16 v[66:69], v[154:157], v[186:189], v[66:69]
	v_mfma_f32_16x16x32_bf16 v[70:73], v[138:141], v[186:189], v[70:73]
	v_mfma_f32_16x16x32_bf16 v[134:137], v[142:145], v[166:169], v[134:137]
	v_mfma_f32_16x16x32_bf16 v[130:133], v[158:161], v[166:169], v[130:133]
	v_mfma_f32_16x16x32_bf16 v[106:109], v[158:161], v[174:177], v[106:109]
	v_mfma_f32_16x16x32_bf16 v[110:113], v[142:145], v[174:177], v[110:113]
	v_mfma_f32_16x16x32_bf16 v[86:89], v[142:145], v[182:185], v[86:89]
	v_mfma_f32_16x16x32_bf16 v[82:85], v[158:161], v[182:185], v[82:85]
	v_mfma_f32_16x16x32_bf16 v[66:69], v[158:161], v[190:193], v[66:69]
	v_mfma_f32_16x16x32_bf16 v[70:73], v[142:145], v[190:193], v[70:73]
	s_setprio 0
	s_barrier
; #define PG8_STAGE(bufoff, gbase, voff) do { _Pragma("unroll") for (int _i = 0; _i < 2; ++_i) \
;         __builtin_amdgcn_global_load_lds((const unsigned*)((const char*)(gbase) + (voff)[_i]), (LAS unsigned*)(lds + (bufoff) + ldsw + _i * 8192), 16, 0, 0); } while (0)
; #define PG8_LDA(dst, b, h) do { _Pragma("unroll") for (int m = 0; m < 4; ++m) _Pragma("unroll") for (int k = 0; k < 2; ++k) dst[m][k] = *(const LAS bf16x8*)(lds + PG8_SA(b, h) + aoff + m * 2048 + k * 1024); } while (0)
; #define PG8_MMA(ai, bj, At, Bt) do { __builtin_amdgcn_s_setprio(1); _Pragma("unroll") for (int m = 0; m < 4; ++m) _Pragma("unroll") for (int n = 0; n < 2; ++n) _Pragma("unroll") for (int k = 0; k < 2; ++k) \
;         acc[ai][bj][m][n] = __builtin_amdgcn_mfma_f32_16x16x32_bf16(Bt[n][k], At[m][k], acc[ai][bj][m][n], 0, 0, 0); __builtin_amdgcn_s_setprio(0); } while (0)
; #define PG8_WAIT_V(n) asm volatile("s_waitcnt vmcnt(" #n ")" ::: "memory")
; #define PG8_WAIT_L(n) asm volatile("s_waitcnt lgkmcnt(" #n ")" ::: "memory")
; #define PG8_BAR __builtin_amdgcn_s_barrier()
; #define PG8_SCHED __builtin_amdgcn_sched_barrier(0)
; template <class Epi, class Sched, bool ALIGN_EPI = false, bool SP2 = false>
; __device__ __forceinline__ void gemm_phase(LAS unsigned char* lds, const Gemm g, const Sched& S, const Epi& E) {
;     ...
;             PG8_LDA(At, 1, 1); PG8_STAGE(PG8_SB(1, 0), b3, voffB); PG8_STAGE(PG8_SB(1, 1), b3 + hstep, voffB); PG8_STAGE(PG8_SA(1, 0), a3, voffA);
;             PG8_WAIT_V(8); PG8_WAIT_L(0); PG8_BAR; PG8_MMA(1, 0, At, B0); PG8_MMA(1, 1, At, B1); PG8_BAR; PG8_SCHED;
;     ...
;         if constexpr (ALIGN_EPI) { if (wr == 0) PG8_BAR; }
	s_add_i32 s22, s49, s7
	v_lshl_add_u64 v[204:205], v[204:205], 0, s[12:13]
	s_mov_b32 m0, s22
	ds_read_b128 v[162:165], v249 offset:49152
	ds_read_b128 v[166:169], v249 offset:50176
	ds_read_b128 v[170:173], v249 offset:51200
	ds_read_b128 v[174:177], v249 offset:52224
	ds_read_b128 v[178:181], v249 offset:53248
	ds_read_b128 v[182:185], v249 offset:54272
	ds_read_b128 v[186:189], v249 offset:55296
	ds_read_b128 v[190:193], v249 offset:56320
	global_load_lds_dwordx4 v[204:205], off
	s_add_i32 m0, s22, 0x2000
	s_add_u32 s22, s26, 0x160080
	v_lshl_add_u64 v[204:205], v[206:207], 0, s[12:13]
	s_addc_u32 s23, s27, 0
	s_add_i32 s26, s50, s7
	global_load_lds_dwordx4 v[204:205], off
	v_lshl_add_u64 v[204:205], s[22:23], 0, v[0:1]
	s_mov_b32 m0, s26
	s_nop 0
	global_load_lds_dwordx4 v[204:205], off
	v_lshl_add_u64 v[204:205], s[22:23], 0, v[194:195]
	s_add_i32 m0, s26, 0x2000
	s_nop 0
	global_load_lds_dwordx4 v[204:205], off
	v_lshl_add_u64 v[204:205], v[208:209], 0, s[12:13]
	s_mov_b32 m0, s35
	s_nop 0
	global_load_lds_dwordx4 v[204:205], off
	v_lshl_add_u64 v[204:205], v[210:211], 0, s[12:13]
	s_mov_b32 m0, s40
	s_nop 0
	global_load_lds_dwordx4 v[204:205], off
	s_waitcnt vmcnt(8)
	s_waitcnt lgkmcnt(0)
	s_barrier
	s_setprio 1
	s_waitcnt lgkmcnt(0)
	v_mfma_f32_16x16x32_bf16 v[62:65], v[90:93], v[162:165], v[62:65]
	v_mfma_f32_16x16x32_bf16 v[58:61], v[114:117], v[162:165], v[58:61]
	v_mfma_f32_16x16x32_bf16 v[42:45], v[114:117], v[170:173], v[42:45]
	v_mfma_f32_16x16x32_bf16 v[46:49], v[90:93], v[170:173], v[46:49]
	v_mfma_f32_16x16x32_bf16 v[30:33], v[90:93], v[178:181], v[30:33]
	v_mfma_f32_16x16x32_bf16 v[26:29], v[114:117], v[178:181], v[26:29]
	v_mfma_f32_16x16x32_bf16 v[10:13], v[114:117], v[186:189], v[10:13]
	v_mfma_f32_16x16x32_bf16 v[14:17], v[90:93], v[186:189], v[14:17]
	v_mfma_f32_16x16x32_bf16 v[62:65], v[102:105], v[166:169], v[62:65]
	v_mfma_f32_16x16x32_bf16 v[58:61], v[126:129], v[166:169], v[58:61]
	v_mfma_f32_16x16x32_bf16 v[42:45], v[126:129], v[174:177], v[42:45]
	v_mfma_f32_16x16x32_bf16 v[46:49], v[102:105], v[174:177], v[46:49]
	v_mfma_f32_16x16x32_bf16 v[30:33], v[102:105], v[182:185], v[30:33]
	v_mfma_f32_16x16x32_bf16 v[26:29], v[126:129], v[182:185], v[26:29]
	v_mfma_f32_16x16x32_bf16 v[10:13], v[126:129], v[190:193], v[10:13]
	v_mfma_f32_16x16x32_bf16 v[14:17], v[102:105], v[190:193], v[14:17]
	s_setprio 0
	s_setprio 1
	v_mfma_f32_16x16x32_bf16 v[54:57], v[138:141], v[162:165], v[54:57]
	v_mfma_f32_16x16x32_bf16 v[50:53], v[154:157], v[162:165], v[50:53]
	v_mfma_f32_16x16x32_bf16 v[34:37], v[154:157], v[170:173], v[34:37]
	v_mfma_f32_16x16x32_bf16 v[38:41], v[138:141], v[170:173], v[38:41]
	v_mfma_f32_16x16x32_bf16 v[22:25], v[138:141], v[178:181], v[22:25]
	v_mfma_f32_16x16x32_bf16 v[18:21], v[154:157], v[178:181], v[18:21]
	v_mfma_f32_16x16x32_bf16 v[2:5], v[154:157], v[186:189], v[2:5]
	v_mfma_f32_16x16x32_bf16 v[6:9], v[138:141], v[186:189], v[6:9]
	v_mfma_f32_16x16x32_bf16 v[54:57], v[142:145], v[166:169], v[54:57]
	v_mfma_f32_16x16x32_bf16 v[50:53], v[158:161], v[166:169], v[50:53]
	v_mfma_f32_16x16x32_bf16 v[34:37], v[158:161], v[174:177], v[34:37]
	v_mfma_f32_16x16x32_bf16 v[38:41], v[142:145], v[174:177], v[38:41]
	v_mfma_f32_16x16x32_bf16 v[22:25], v[142:145], v[182:185], v[22:25]
	v_mfma_f32_16x16x32_bf16 v[18:21], v[158:161], v[182:185], v[18:21]
	v_mfma_f32_16x16x32_bf16 v[2:5], v[158:161], v[190:193], v[2:5]
	v_mfma_f32_16x16x32_bf16 v[6:9], v[142:145], v[190:193], v[6:9]
	s_setprio 0
	s_barrier
	s_add_i32 s48, s48, 2
	s_add_u32 s46, s46, 0x100
	s_addc_u32 s47, s47, 0
	s_cmpk_gt_u32 s48, 0x55
	s_mov_b64 s[22:23], s[24:25]
	s_cbranch_scc0 .LBB0_1007
	s_and_b64 vcc, exec, s[18:19]
	s_cbranch_vccz .LBB0_1010
	s_barrier
